# ATTN P.V section fully unrolled and software-pipelined: V gathers issued one 64-key batch ahead, 32-bit offsets with SGPR base
# speedup vs baseline: 1.0510x; 1.0124x over previous
; DI void attn_item(const P& p, int b, int kvh, int quad4, char* smem, const AttnPre& pre) {
;     ...
;   const unsigned char* vb = p.v8 + ((size_t)b * SEQ) * 256 + kvh * 128 + r * 8;
; #pragma unroll 1
;   for (int n0 = 0; n0 < 256; n0 += 64) {
;     uint2 vv[16];
; #pragma unroll
;     for (int u = 0; u < 16; ++u) vv[u] = *(const uint2*)(vb + (size_t)idx[n0 + 4 * u + quad] * 256);
; #pragma unroll
;     for (int u = 0; u < 16; ++u) {
;       const float4 p4 = *(const float4*)(L + (n0 + 4 * u + quad) * 4);
;       const f32x2_t c0 = __builtin_amdgcn_cvt_pk_f32_fp8((int)vv[u].x, false), c1 = __builtin_amdgcn_cvt_pk_f32_fp8((int)vv[u].x, true);
;       const f32x2_t c2 = __builtin_amdgcn_cvt_pk_f32_fp8((int)vv[u].y, false), c3 = __builtin_amdgcn_cvt_pk_f32_fp8((int)vv[u].y, true);
;       const float vf[8] = {c0.x, c0.y, c1.x, c1.y, c2.x, c2.y, c3.x, c3.y};
; #pragma unroll
;       for (int e = 0; e < 8; ++e) {
;         o[0][e] = fmaf(p4.x, vf[e], o[0][e]); o[1][e] = fmaf(p4.y, vf[e], o[1][e]);
;         o[2][e] = fmaf(p4.z, vf[e], o[2][e]); o[3][e] = fmaf(p4.w, vf[e], o[3][e]);
;       }
.LBB0_346:
	v_readlane_b32 s6, v250, 15
	v_readlane_b32 s7, v250, 16
	s_add_u32 s6, s6, s10
	s_addc_u32 s7, s7, s11
	v_subrev_u32_e32 v168, s6, v24
	ds_read2_b32 v[152:153], v86 offset0:0 offset1:4
	ds_read2_b32 v[154:155], v86 offset0:8 offset1:12
	ds_read2_b32 v[156:157], v86 offset0:16 offset1:20
	ds_read2_b32 v[158:159], v86 offset0:24 offset1:28
	ds_read2_b32 v[160:161], v86 offset0:32 offset1:36
	ds_read2_b32 v[162:163], v86 offset0:40 offset1:44
	ds_read2_b32 v[164:165], v86 offset0:48 offset1:52
	ds_read2_b32 v[166:167], v86 offset0:56 offset1:60
	s_waitcnt lgkmcnt(0)
	v_lshl_add_u32 v152, v152, 8, v168
	v_lshl_add_u32 v153, v153, 8, v168
	v_lshl_add_u32 v154, v154, 8, v168
	v_lshl_add_u32 v155, v155, 8, v168
	v_lshl_add_u32 v156, v156, 8, v168
	v_lshl_add_u32 v157, v157, 8, v168
	v_lshl_add_u32 v158, v158, 8, v168
	v_lshl_add_u32 v159, v159, 8, v168
	v_lshl_add_u32 v160, v160, 8, v168
	v_lshl_add_u32 v161, v161, 8, v168
	v_lshl_add_u32 v162, v162, 8, v168
	v_lshl_add_u32 v163, v163, 8, v168
	v_lshl_add_u32 v164, v164, 8, v168
	v_lshl_add_u32 v165, v165, 8, v168
	v_lshl_add_u32 v166, v166, 8, v168
	v_lshl_add_u32 v167, v167, 8, v168
	global_load_dwordx2 v[50:51], v152, s[6:7]
	global_load_dwordx2 v[52:53], v153, s[6:7]
	global_load_dwordx2 v[54:55], v154, s[6:7]
	global_load_dwordx2 v[56:57], v155, s[6:7]
	global_load_dwordx2 v[58:59], v156, s[6:7]
	global_load_dwordx2 v[60:61], v157, s[6:7]
	global_load_dwordx2 v[62:63], v158, s[6:7]
	global_load_dwordx2 v[64:65], v159, s[6:7]
	global_load_dwordx2 v[66:67], v160, s[6:7]
	global_load_dwordx2 v[68:69], v161, s[6:7]
	global_load_dwordx2 v[70:71], v162, s[6:7]
	global_load_dwordx2 v[72:73], v163, s[6:7]
	global_load_dwordx2 v[74:75], v164, s[6:7]
	global_load_dwordx2 v[76:77], v165, s[6:7]
	global_load_dwordx2 v[78:79], v166, s[6:7]
	global_load_dwordx2 v[80:81], v167, s[6:7]
	ds_read_b128 v[92:95], v87
	ds_read2_b32 v[152:153], v86 offset0:64 offset1:68
	ds_read2_b32 v[154:155], v86 offset0:72 offset1:76
	ds_read2_b32 v[156:157], v86 offset0:80 offset1:84
	ds_read2_b32 v[158:159], v86 offset0:88 offset1:92
	ds_read2_b32 v[160:161], v86 offset0:96 offset1:100
	ds_read2_b32 v[162:163], v86 offset0:104 offset1:108
	ds_read2_b32 v[164:165], v86 offset0:112 offset1:116
	ds_read2_b32 v[166:167], v86 offset0:120 offset1:124
	s_waitcnt lgkmcnt(0)
	v_lshl_add_u32 v152, v152, 8, v168
	v_lshl_add_u32 v153, v153, 8, v168
	v_lshl_add_u32 v154, v154, 8, v168
	v_lshl_add_u32 v155, v155, 8, v168
	v_lshl_add_u32 v156, v156, 8, v168
	v_lshl_add_u32 v157, v157, 8, v168
	v_lshl_add_u32 v158, v158, 8, v168
	v_lshl_add_u32 v159, v159, 8, v168
	v_lshl_add_u32 v160, v160, 8, v168
	v_lshl_add_u32 v161, v161, 8, v168
	v_lshl_add_u32 v162, v162, 8, v168
	v_lshl_add_u32 v163, v163, 8, v168
	v_lshl_add_u32 v164, v164, 8, v168
	v_lshl_add_u32 v165, v165, 8, v168
	v_lshl_add_u32 v166, v166, 8, v168
	v_lshl_add_u32 v167, v167, 8, v168
	global_load_dwordx2 v[120:121], v152, s[6:7]
	global_load_dwordx2 v[122:123], v153, s[6:7]
	global_load_dwordx2 v[124:125], v154, s[6:7]
	global_load_dwordx2 v[126:127], v155, s[6:7]
	global_load_dwordx2 v[128:129], v156, s[6:7]
	global_load_dwordx2 v[130:131], v157, s[6:7]
	global_load_dwordx2 v[132:133], v158, s[6:7]
	global_load_dwordx2 v[134:135], v159, s[6:7]
	global_load_dwordx2 v[136:137], v160, s[6:7]
	global_load_dwordx2 v[138:139], v161, s[6:7]
	global_load_dwordx2 v[140:141], v162, s[6:7]
	global_load_dwordx2 v[142:143], v163, s[6:7]
	global_load_dwordx2 v[144:145], v164, s[6:7]
	global_load_dwordx2 v[146:147], v165, s[6:7]
	global_load_dwordx2 v[148:149], v166, s[6:7]
	global_load_dwordx2 v[150:151], v167, s[6:7]
	ds_read_b128 v[96:99], v87 offset:64
	s_waitcnt vmcnt(31) lgkmcnt(1)
	v_cvt_pk_f32_fp8_e32 v[100:101], v50
	v_cvt_pk_f32_fp8_sdwa v[102:103], v50 src0_sel:WORD_1
	v_cvt_pk_f32_fp8_e32 v[104:105], v51
	v_cvt_pk_f32_fp8_sdwa v[106:107], v51 src0_sel:WORD_1
	v_pk_fma_f32 v[48:49], v[92:93], v[100:101], v[48:49] op_sel_hi:[0,1,1]
	v_pk_fma_f32 v[44:45], v[92:93], v[100:101], v[44:45] op_sel:[1,0,0]
	v_pk_fma_f32 v[38:39], v[94:95], v[100:101], v[38:39] op_sel_hi:[0,1,1]
	v_pk_fma_f32 v[30:31], v[94:95], v[100:101], v[30:31] op_sel:[1,0,0]
	v_pk_fma_f32 v[46:47], v[92:93], v[102:103], v[46:47] op_sel_hi:[0,1,1]
	v_pk_fma_f32 v[42:43], v[92:93], v[102:103], v[42:43] op_sel:[1,0,0]
	v_pk_fma_f32 v[34:35], v[94:95], v[102:103], v[34:35] op_sel_hi:[0,1,1]
	v_pk_fma_f32 v[26:27], v[94:95], v[102:103], v[26:27] op_sel:[1,0,0]
	v_pk_fma_f32 v[40:41], v[92:93], v[104:105], v[40:41] op_sel_hi:[0,1,1]
	v_pk_fma_f32 v[32:33], v[92:93], v[104:105], v[32:33] op_sel:[1,0,0]
	v_pk_fma_f32 v[22:23], v[94:95], v[104:105], v[22:23] op_sel_hi:[0,1,1]
	v_pk_fma_f32 v[18:19], v[94:95], v[104:105], v[18:19] op_sel:[1,0,0]
	v_pk_fma_f32 v[36:37], v[92:93], v[106:107], v[36:37] op_sel_hi:[0,1,1]
	v_pk_fma_f32 v[28:29], v[92:93], v[106:107], v[28:29] op_sel:[1,0,0]
	v_pk_fma_f32 v[20:21], v[94:95], v[106:107], v[20:21] op_sel_hi:[0,1,1]
	v_pk_fma_f32 v[16:17], v[94:95], v[106:107], v[16:17] op_sel:[1,0,0]
	ds_read_b128 v[92:95], v87 offset:128
	s_waitcnt vmcnt(30) lgkmcnt(1)
; DI void attn_item(const P& p, int b, int kvh, int quad4, char* smem, const AttnPre& pre) {
;     ...
;     for (int u = 0; u < 16; ++u) vv[u] = *(const uint2*)(vb + (size_t)idx[n0 + 4 * u + quad] * 256);
; #pragma unroll
;     for (int u = 0; u < 16; ++u) {
;       const float4 p4 = *(const float4*)(L + (n0 + 4 * u + quad) * 4);
;       const f32x2_t c0 = __builtin_amdgcn_cvt_pk_f32_fp8((int)vv[u].x, false), c1 = __builtin_amdgcn_cvt_pk_f32_fp8((int)vv[u].x, true);
;       const f32x2_t c2 = __builtin_amdgcn_cvt_pk_f32_fp8((int)vv[u].y, false), c3 = __builtin_amdgcn_cvt_pk_f32_fp8((int)vv[u].y, true);
;       const float vf[8] = {c0.x, c0.y, c1.x, c1.y, c2.x, c2.y, c3.x, c3.y};
; #pragma unroll
;       for (int e = 0; e < 8; ++e) {
;         o[0][e] = fmaf(p4.x, vf[e], o[0][e]); o[1][e] = fmaf(p4.y, vf[e], o[1][e]);
;         o[2][e] = fmaf(p4.z, vf[e], o[2][e]); o[3][e] = fmaf(p4.w, vf[e], o[3][e]);
;       }
	v_cvt_pk_f32_fp8_e32 v[100:101], v52
	v_cvt_pk_f32_fp8_sdwa v[102:103], v52 src0_sel:WORD_1
	v_cvt_pk_f32_fp8_e32 v[104:105], v53
	v_cvt_pk_f32_fp8_sdwa v[106:107], v53 src0_sel:WORD_1
	v_pk_fma_f32 v[48:49], v[96:97], v[100:101], v[48:49] op_sel_hi:[0,1,1]
	v_pk_fma_f32 v[44:45], v[96:97], v[100:101], v[44:45] op_sel:[1,0,0]
	v_pk_fma_f32 v[38:39], v[98:99], v[100:101], v[38:39] op_sel_hi:[0,1,1]
	v_pk_fma_f32 v[30:31], v[98:99], v[100:101], v[30:31] op_sel:[1,0,0]
	v_pk_fma_f32 v[46:47], v[96:97], v[102:103], v[46:47] op_sel_hi:[0,1,1]
	v_pk_fma_f32 v[42:43], v[96:97], v[102:103], v[42:43] op_sel:[1,0,0]
	v_pk_fma_f32 v[34:35], v[98:99], v[102:103], v[34:35] op_sel_hi:[0,1,1]
	v_pk_fma_f32 v[26:27], v[98:99], v[102:103], v[26:27] op_sel:[1,0,0]
	v_pk_fma_f32 v[40:41], v[96:97], v[104:105], v[40:41] op_sel_hi:[0,1,1]
	v_pk_fma_f32 v[32:33], v[96:97], v[104:105], v[32:33] op_sel:[1,0,0]
	v_pk_fma_f32 v[22:23], v[98:99], v[104:105], v[22:23] op_sel_hi:[0,1,1]
	v_pk_fma_f32 v[18:19], v[98:99], v[104:105], v[18:19] op_sel:[1,0,0]
	v_pk_fma_f32 v[36:37], v[96:97], v[106:107], v[36:37] op_sel_hi:[0,1,1]
	v_pk_fma_f32 v[28:29], v[96:97], v[106:107], v[28:29] op_sel:[1,0,0]
	v_pk_fma_f32 v[20:21], v[98:99], v[106:107], v[20:21] op_sel_hi:[0,1,1]
	v_pk_fma_f32 v[16:17], v[98:99], v[106:107], v[16:17] op_sel:[1,0,0]
	ds_read_b128 v[96:99], v87 offset:192
	s_waitcnt vmcnt(29) lgkmcnt(1)
	v_cvt_pk_f32_fp8_e32 v[100:101], v54
	v_cvt_pk_f32_fp8_sdwa v[102:103], v54 src0_sel:WORD_1
	v_cvt_pk_f32_fp8_e32 v[104:105], v55
	v_cvt_pk_f32_fp8_sdwa v[106:107], v55 src0_sel:WORD_1
	v_pk_fma_f32 v[48:49], v[92:93], v[100:101], v[48:49] op_sel_hi:[0,1,1]
	v_pk_fma_f32 v[44:45], v[92:93], v[100:101], v[44:45] op_sel:[1,0,0]
	v_pk_fma_f32 v[38:39], v[94:95], v[100:101], v[38:39] op_sel_hi:[0,1,1]
	v_pk_fma_f32 v[30:31], v[94:95], v[100:101], v[30:31] op_sel:[1,0,0]
	v_pk_fma_f32 v[46:47], v[92:93], v[102:103], v[46:47] op_sel_hi:[0,1,1]
	v_pk_fma_f32 v[42:43], v[92:93], v[102:103], v[42:43] op_sel:[1,0,0]
	v_pk_fma_f32 v[34:35], v[94:95], v[102:103], v[34:35] op_sel_hi:[0,1,1]
	v_pk_fma_f32 v[26:27], v[94:95], v[102:103], v[26:27] op_sel:[1,0,0]
	v_pk_fma_f32 v[40:41], v[92:93], v[104:105], v[40:41] op_sel_hi:[0,1,1]
	v_pk_fma_f32 v[32:33], v[92:93], v[104:105], v[32:33] op_sel:[1,0,0]
	v_pk_fma_f32 v[22:23], v[94:95], v[104:105], v[22:23] op_sel_hi:[0,1,1]
	v_pk_fma_f32 v[18:19], v[94:95], v[104:105], v[18:19] op_sel:[1,0,0]
	v_pk_fma_f32 v[36:37], v[92:93], v[106:107], v[36:37] op_sel_hi:[0,1,1]
	v_pk_fma_f32 v[28:29], v[92:93], v[106:107], v[28:29] op_sel:[1,0,0]
	v_pk_fma_f32 v[20:21], v[94:95], v[106:107], v[20:21] op_sel_hi:[0,1,1]
	v_pk_fma_f32 v[16:17], v[94:95], v[106:107], v[16:17] op_sel:[1,0,0]
	ds_read_b128 v[92:95], v87 offset:256
	s_waitcnt vmcnt(28) lgkmcnt(1)
	v_cvt_pk_f32_fp8_e32 v[100:101], v56
	v_cvt_pk_f32_fp8_sdwa v[102:103], v56 src0_sel:WORD_1
	v_cvt_pk_f32_fp8_e32 v[104:105], v57
	v_cvt_pk_f32_fp8_sdwa v[106:107], v57 src0_sel:WORD_1
	v_pk_fma_f32 v[48:49], v[96:97], v[100:101], v[48:49] op_sel_hi:[0,1,1]
	v_pk_fma_f32 v[44:45], v[96:97], v[100:101], v[44:45] op_sel:[1,0,0]
	v_pk_fma_f32 v[38:39], v[98:99], v[100:101], v[38:39] op_sel_hi:[0,1,1]
	v_pk_fma_f32 v[30:31], v[98:99], v[100:101], v[30:31] op_sel:[1,0,0]
	v_pk_fma_f32 v[46:47], v[96:97], v[102:103], v[46:47] op_sel_hi:[0,1,1]
	v_pk_fma_f32 v[42:43], v[96:97], v[102:103], v[42:43] op_sel:[1,0,0]
	v_pk_fma_f32 v[34:35], v[98:99], v[102:103], v[34:35] op_sel_hi:[0,1,1]
	v_pk_fma_f32 v[26:27], v[98:99], v[102:103], v[26:27] op_sel:[1,0,0]
	v_pk_fma_f32 v[40:41], v[96:97], v[104:105], v[40:41] op_sel_hi:[0,1,1]
	v_pk_fma_f32 v[32:33], v[96:97], v[104:105], v[32:33] op_sel:[1,0,0]
	v_pk_fma_f32 v[22:23], v[98:99], v[104:105], v[22:23] op_sel_hi:[0,1,1]
	v_pk_fma_f32 v[18:19], v[98:99], v[104:105], v[18:19] op_sel:[1,0,0]
	v_pk_fma_f32 v[36:37], v[96:97], v[106:107], v[36:37] op_sel_hi:[0,1,1]
	v_pk_fma_f32 v[28:29], v[96:97], v[106:107], v[28:29] op_sel:[1,0,0]
	v_pk_fma_f32 v[20:21], v[98:99], v[106:107], v[20:21] op_sel_hi:[0,1,1]
	v_pk_fma_f32 v[16:17], v[98:99], v[106:107], v[16:17] op_sel:[1,0,0]
	ds_read_b128 v[96:99], v87 offset:320
	s_waitcnt vmcnt(27) lgkmcnt(1)
	v_cvt_pk_f32_fp8_e32 v[100:101], v58
	v_cvt_pk_f32_fp8_sdwa v[102:103], v58 src0_sel:WORD_1
	v_cvt_pk_f32_fp8_e32 v[104:105], v59
	v_cvt_pk_f32_fp8_sdwa v[106:107], v59 src0_sel:WORD_1
	v_pk_fma_f32 v[48:49], v[92:93], v[100:101], v[48:49] op_sel_hi:[0,1,1]
	v_pk_fma_f32 v[44:45], v[92:93], v[100:101], v[44:45] op_sel:[1,0,0]
	v_pk_fma_f32 v[38:39], v[94:95], v[100:101], v[38:39] op_sel_hi:[0,1,1]
	v_pk_fma_f32 v[30:31], v[94:95], v[100:101], v[30:31] op_sel:[1,0,0]
	v_pk_fma_f32 v[46:47], v[92:93], v[102:103], v[46:47] op_sel_hi:[0,1,1]
	v_pk_fma_f32 v[42:43], v[92:93], v[102:103], v[42:43] op_sel:[1,0,0]
	v_pk_fma_f32 v[34:35], v[94:95], v[102:103], v[34:35] op_sel_hi:[0,1,1]
	v_pk_fma_f32 v[26:27], v[94:95], v[102:103], v[26:27] op_sel:[1,0,0]
	v_pk_fma_f32 v[40:41], v[92:93], v[104:105], v[40:41] op_sel_hi:[0,1,1]
	v_pk_fma_f32 v[32:33], v[92:93], v[104:105], v[32:33] op_sel:[1,0,0]
	v_pk_fma_f32 v[22:23], v[94:95], v[104:105], v[22:23] op_sel_hi:[0,1,1]
	v_pk_fma_f32 v[18:19], v[94:95], v[104:105], v[18:19] op_sel:[1,0,0]
	v_pk_fma_f32 v[36:37], v[92:93], v[106:107], v[36:37] op_sel_hi:[0,1,1]
	v_pk_fma_f32 v[28:29], v[92:93], v[106:107], v[28:29] op_sel:[1,0,0]
	v_pk_fma_f32 v[20:21], v[94:95], v[106:107], v[20:21] op_sel_hi:[0,1,1]
	v_pk_fma_f32 v[16:17], v[94:95], v[106:107], v[16:17] op_sel:[1,0,0]
	ds_read_b128 v[92:95], v87 offset:384
	s_waitcnt vmcnt(26) lgkmcnt(1)
; DI void attn_item(const P& p, int b, int kvh, int quad4, char* smem, const AttnPre& pre) {
;     ...
;     for (int u = 0; u < 16; ++u) vv[u] = *(const uint2*)(vb + (size_t)idx[n0 + 4 * u + quad] * 256);
; #pragma unroll
;     for (int u = 0; u < 16; ++u) {
;       const float4 p4 = *(const float4*)(L + (n0 + 4 * u + quad) * 4);
;       const f32x2_t c0 = __builtin_amdgcn_cvt_pk_f32_fp8((int)vv[u].x, false), c1 = __builtin_amdgcn_cvt_pk_f32_fp8((int)vv[u].x, true);
;       const f32x2_t c2 = __builtin_amdgcn_cvt_pk_f32_fp8((int)vv[u].y, false), c3 = __builtin_amdgcn_cvt_pk_f32_fp8((int)vv[u].y, true);
;       const float vf[8] = {c0.x, c0.y, c1.x, c1.y, c2.x, c2.y, c3.x, c3.y};
; #pragma unroll
;       for (int e = 0; e < 8; ++e) {
;         o[0][e] = fmaf(p4.x, vf[e], o[0][e]); o[1][e] = fmaf(p4.y, vf[e], o[1][e]);
;         o[2][e] = fmaf(p4.z, vf[e], o[2][e]); o[3][e] = fmaf(p4.w, vf[e], o[3][e]);
;       }
	v_cvt_pk_f32_fp8_e32 v[100:101], v60
	v_cvt_pk_f32_fp8_sdwa v[102:103], v60 src0_sel:WORD_1
	v_cvt_pk_f32_fp8_e32 v[104:105], v61
	v_cvt_pk_f32_fp8_sdwa v[106:107], v61 src0_sel:WORD_1
	v_pk_fma_f32 v[48:49], v[96:97], v[100:101], v[48:49] op_sel_hi:[0,1,1]
	v_pk_fma_f32 v[44:45], v[96:97], v[100:101], v[44:45] op_sel:[1,0,0]
	v_pk_fma_f32 v[38:39], v[98:99], v[100:101], v[38:39] op_sel_hi:[0,1,1]
	v_pk_fma_f32 v[30:31], v[98:99], v[100:101], v[30:31] op_sel:[1,0,0]
	v_pk_fma_f32 v[46:47], v[96:97], v[102:103], v[46:47] op_sel_hi:[0,1,1]
	v_pk_fma_f32 v[42:43], v[96:97], v[102:103], v[42:43] op_sel:[1,0,0]
	v_pk_fma_f32 v[34:35], v[98:99], v[102:103], v[34:35] op_sel_hi:[0,1,1]
	v_pk_fma_f32 v[26:27], v[98:99], v[102:103], v[26:27] op_sel:[1,0,0]
	v_pk_fma_f32 v[40:41], v[96:97], v[104:105], v[40:41] op_sel_hi:[0,1,1]
	v_pk_fma_f32 v[32:33], v[96:97], v[104:105], v[32:33] op_sel:[1,0,0]
	v_pk_fma_f32 v[22:23], v[98:99], v[104:105], v[22:23] op_sel_hi:[0,1,1]
	v_pk_fma_f32 v[18:19], v[98:99], v[104:105], v[18:19] op_sel:[1,0,0]
	v_pk_fma_f32 v[36:37], v[96:97], v[106:107], v[36:37] op_sel_hi:[0,1,1]
	v_pk_fma_f32 v[28:29], v[96:97], v[106:107], v[28:29] op_sel:[1,0,0]
	v_pk_fma_f32 v[20:21], v[98:99], v[106:107], v[20:21] op_sel_hi:[0,1,1]
	v_pk_fma_f32 v[16:17], v[98:99], v[106:107], v[16:17] op_sel:[1,0,0]
	ds_read_b128 v[96:99], v87 offset:448
	s_waitcnt vmcnt(25) lgkmcnt(1)
	v_cvt_pk_f32_fp8_e32 v[100:101], v62
	v_cvt_pk_f32_fp8_sdwa v[102:103], v62 src0_sel:WORD_1
	v_cvt_pk_f32_fp8_e32 v[104:105], v63
	v_cvt_pk_f32_fp8_sdwa v[106:107], v63 src0_sel:WORD_1
	v_pk_fma_f32 v[48:49], v[92:93], v[100:101], v[48:49] op_sel_hi:[0,1,1]
	v_pk_fma_f32 v[44:45], v[92:93], v[100:101], v[44:45] op_sel:[1,0,0]
	v_pk_fma_f32 v[38:39], v[94:95], v[100:101], v[38:39] op_sel_hi:[0,1,1]
	v_pk_fma_f32 v[30:31], v[94:95], v[100:101], v[30:31] op_sel:[1,0,0]
	v_pk_fma_f32 v[46:47], v[92:93], v[102:103], v[46:47] op_sel_hi:[0,1,1]
	v_pk_fma_f32 v[42:43], v[92:93], v[102:103], v[42:43] op_sel:[1,0,0]
	v_pk_fma_f32 v[34:35], v[94:95], v[102:103], v[34:35] op_sel_hi:[0,1,1]
	v_pk_fma_f32 v[26:27], v[94:95], v[102:103], v[26:27] op_sel:[1,0,0]
	v_pk_fma_f32 v[40:41], v[92:93], v[104:105], v[40:41] op_sel_hi:[0,1,1]
	v_pk_fma_f32 v[32:33], v[92:93], v[104:105], v[32:33] op_sel:[1,0,0]
	v_pk_fma_f32 v[22:23], v[94:95], v[104:105], v[22:23] op_sel_hi:[0,1,1]
	v_pk_fma_f32 v[18:19], v[94:95], v[104:105], v[18:19] op_sel:[1,0,0]
	v_pk_fma_f32 v[36:37], v[92:93], v[106:107], v[36:37] op_sel_hi:[0,1,1]
	v_pk_fma_f32 v[28:29], v[92:93], v[106:107], v[28:29] op_sel:[1,0,0]
	v_pk_fma_f32 v[20:21], v[94:95], v[106:107], v[20:21] op_sel_hi:[0,1,1]
	v_pk_fma_f32 v[16:17], v[94:95], v[106:107], v[16:17] op_sel:[1,0,0]
	ds_read_b128 v[92:95], v87 offset:512
	s_waitcnt vmcnt(24) lgkmcnt(1)
	v_cvt_pk_f32_fp8_e32 v[100:101], v64
	v_cvt_pk_f32_fp8_sdwa v[102:103], v64 src0_sel:WORD_1
	v_cvt_pk_f32_fp8_e32 v[104:105], v65
	v_cvt_pk_f32_fp8_sdwa v[106:107], v65 src0_sel:WORD_1
	v_pk_fma_f32 v[48:49], v[96:97], v[100:101], v[48:49] op_sel_hi:[0,1,1]
	v_pk_fma_f32 v[44:45], v[96:97], v[100:101], v[44:45] op_sel:[1,0,0]
	v_pk_fma_f32 v[38:39], v[98:99], v[100:101], v[38:39] op_sel_hi:[0,1,1]
	v_pk_fma_f32 v[30:31], v[98:99], v[100:101], v[30:31] op_sel:[1,0,0]
	v_pk_fma_f32 v[46:47], v[96:97], v[102:103], v[46:47] op_sel_hi:[0,1,1]
	v_pk_fma_f32 v[42:43], v[96:97], v[102:103], v[42:43] op_sel:[1,0,0]
	v_pk_fma_f32 v[34:35], v[98:99], v[102:103], v[34:35] op_sel_hi:[0,1,1]
	v_pk_fma_f32 v[26:27], v[98:99], v[102:103], v[26:27] op_sel:[1,0,0]
	v_pk_fma_f32 v[40:41], v[96:97], v[104:105], v[40:41] op_sel_hi:[0,1,1]
	v_pk_fma_f32 v[32:33], v[96:97], v[104:105], v[32:33] op_sel:[1,0,0]
	v_pk_fma_f32 v[22:23], v[98:99], v[104:105], v[22:23] op_sel_hi:[0,1,1]
	v_pk_fma_f32 v[18:19], v[98:99], v[104:105], v[18:19] op_sel:[1,0,0]
	v_pk_fma_f32 v[36:37], v[96:97], v[106:107], v[36:37] op_sel_hi:[0,1,1]
	v_pk_fma_f32 v[28:29], v[96:97], v[106:107], v[28:29] op_sel:[1,0,0]
	v_pk_fma_f32 v[20:21], v[98:99], v[106:107], v[20:21] op_sel_hi:[0,1,1]
	v_pk_fma_f32 v[16:17], v[98:99], v[106:107], v[16:17] op_sel:[1,0,0]
	ds_read_b128 v[96:99], v87 offset:576
	s_waitcnt vmcnt(23) lgkmcnt(1)
	v_cvt_pk_f32_fp8_e32 v[100:101], v66
	v_cvt_pk_f32_fp8_sdwa v[102:103], v66 src0_sel:WORD_1
	v_cvt_pk_f32_fp8_e32 v[104:105], v67
	v_cvt_pk_f32_fp8_sdwa v[106:107], v67 src0_sel:WORD_1
	v_pk_fma_f32 v[48:49], v[92:93], v[100:101], v[48:49] op_sel_hi:[0,1,1]
	v_pk_fma_f32 v[44:45], v[92:93], v[100:101], v[44:45] op_sel:[1,0,0]
	v_pk_fma_f32 v[38:39], v[94:95], v[100:101], v[38:39] op_sel_hi:[0,1,1]
	v_pk_fma_f32 v[30:31], v[94:95], v[100:101], v[30:31] op_sel:[1,0,0]
	v_pk_fma_f32 v[46:47], v[92:93], v[102:103], v[46:47] op_sel_hi:[0,1,1]
	v_pk_fma_f32 v[42:43], v[92:93], v[102:103], v[42:43] op_sel:[1,0,0]
	v_pk_fma_f32 v[34:35], v[94:95], v[102:103], v[34:35] op_sel_hi:[0,1,1]
	v_pk_fma_f32 v[26:27], v[94:95], v[102:103], v[26:27] op_sel:[1,0,0]
	v_pk_fma_f32 v[40:41], v[92:93], v[104:105], v[40:41] op_sel_hi:[0,1,1]
	v_pk_fma_f32 v[32:33], v[92:93], v[104:105], v[32:33] op_sel:[1,0,0]
	v_pk_fma_f32 v[22:23], v[94:95], v[104:105], v[22:23] op_sel_hi:[0,1,1]
	v_pk_fma_f32 v[18:19], v[94:95], v[104:105], v[18:19] op_sel:[1,0,0]
	v_pk_fma_f32 v[36:37], v[92:93], v[106:107], v[36:37] op_sel_hi:[0,1,1]
	v_pk_fma_f32 v[28:29], v[92:93], v[106:107], v[28:29] op_sel:[1,0,0]
	v_pk_fma_f32 v[20:21], v[94:95], v[106:107], v[20:21] op_sel_hi:[0,1,1]
	v_pk_fma_f32 v[16:17], v[94:95], v[106:107], v[16:17] op_sel:[1,0,0]
	ds_read_b128 v[92:95], v87 offset:640
	s_waitcnt vmcnt(22) lgkmcnt(1)
; DI void attn_item(const P& p, int b, int kvh, int quad4, char* smem, const AttnPre& pre) {
;     ...
;     for (int u = 0; u < 16; ++u) vv[u] = *(const uint2*)(vb + (size_t)idx[n0 + 4 * u + quad] * 256);
; #pragma unroll
;     for (int u = 0; u < 16; ++u) {
;       const float4 p4 = *(const float4*)(L + (n0 + 4 * u + quad) * 4);
;       const f32x2_t c0 = __builtin_amdgcn_cvt_pk_f32_fp8((int)vv[u].x, false), c1 = __builtin_amdgcn_cvt_pk_f32_fp8((int)vv[u].x, true);
;       const f32x2_t c2 = __builtin_amdgcn_cvt_pk_f32_fp8((int)vv[u].y, false), c3 = __builtin_amdgcn_cvt_pk_f32_fp8((int)vv[u].y, true);
;       const float vf[8] = {c0.x, c0.y, c1.x, c1.y, c2.x, c2.y, c3.x, c3.y};
; #pragma unroll
;       for (int e = 0; e < 8; ++e) {
;         o[0][e] = fmaf(p4.x, vf[e], o[0][e]); o[1][e] = fmaf(p4.y, vf[e], o[1][e]);
;         o[2][e] = fmaf(p4.z, vf[e], o[2][e]); o[3][e] = fmaf(p4.w, vf[e], o[3][e]);
;       }
	v_cvt_pk_f32_fp8_e32 v[100:101], v68
	v_cvt_pk_f32_fp8_sdwa v[102:103], v68 src0_sel:WORD_1
	v_cvt_pk_f32_fp8_e32 v[104:105], v69
	v_cvt_pk_f32_fp8_sdwa v[106:107], v69 src0_sel:WORD_1
	v_pk_fma_f32 v[48:49], v[96:97], v[100:101], v[48:49] op_sel_hi:[0,1,1]
	v_pk_fma_f32 v[44:45], v[96:97], v[100:101], v[44:45] op_sel:[1,0,0]
	v_pk_fma_f32 v[38:39], v[98:99], v[100:101], v[38:39] op_sel_hi:[0,1,1]
	v_pk_fma_f32 v[30:31], v[98:99], v[100:101], v[30:31] op_sel:[1,0,0]
	v_pk_fma_f32 v[46:47], v[96:97], v[102:103], v[46:47] op_sel_hi:[0,1,1]
	v_pk_fma_f32 v[42:43], v[96:97], v[102:103], v[42:43] op_sel:[1,0,0]
	v_pk_fma_f32 v[34:35], v[98:99], v[102:103], v[34:35] op_sel_hi:[0,1,1]
	v_pk_fma_f32 v[26:27], v[98:99], v[102:103], v[26:27] op_sel:[1,0,0]
	v_pk_fma_f32 v[40:41], v[96:97], v[104:105], v[40:41] op_sel_hi:[0,1,1]
	v_pk_fma_f32 v[32:33], v[96:97], v[104:105], v[32:33] op_sel:[1,0,0]
	v_pk_fma_f32 v[22:23], v[98:99], v[104:105], v[22:23] op_sel_hi:[0,1,1]
	v_pk_fma_f32 v[18:19], v[98:99], v[104:105], v[18:19] op_sel:[1,0,0]
	v_pk_fma_f32 v[36:37], v[96:97], v[106:107], v[36:37] op_sel_hi:[0,1,1]
	v_pk_fma_f32 v[28:29], v[96:97], v[106:107], v[28:29] op_sel:[1,0,0]
	v_pk_fma_f32 v[20:21], v[98:99], v[106:107], v[20:21] op_sel_hi:[0,1,1]
	v_pk_fma_f32 v[16:17], v[98:99], v[106:107], v[16:17] op_sel:[1,0,0]
	ds_read_b128 v[96:99], v87 offset:704
	s_waitcnt vmcnt(21) lgkmcnt(1)
	v_cvt_pk_f32_fp8_e32 v[100:101], v70
	v_cvt_pk_f32_fp8_sdwa v[102:103], v70 src0_sel:WORD_1
	v_cvt_pk_f32_fp8_e32 v[104:105], v71
	v_cvt_pk_f32_fp8_sdwa v[106:107], v71 src0_sel:WORD_1
	v_pk_fma_f32 v[48:49], v[92:93], v[100:101], v[48:49] op_sel_hi:[0,1,1]
	v_pk_fma_f32 v[44:45], v[92:93], v[100:101], v[44:45] op_sel:[1,0,0]
	v_pk_fma_f32 v[38:39], v[94:95], v[100:101], v[38:39] op_sel_hi:[0,1,1]
	v_pk_fma_f32 v[30:31], v[94:95], v[100:101], v[30:31] op_sel:[1,0,0]
	v_pk_fma_f32 v[46:47], v[92:93], v[102:103], v[46:47] op_sel_hi:[0,1,1]
	v_pk_fma_f32 v[42:43], v[92:93], v[102:103], v[42:43] op_sel:[1,0,0]
	v_pk_fma_f32 v[34:35], v[94:95], v[102:103], v[34:35] op_sel_hi:[0,1,1]
	v_pk_fma_f32 v[26:27], v[94:95], v[102:103], v[26:27] op_sel:[1,0,0]
	v_pk_fma_f32 v[40:41], v[92:93], v[104:105], v[40:41] op_sel_hi:[0,1,1]
	v_pk_fma_f32 v[32:33], v[92:93], v[104:105], v[32:33] op_sel:[1,0,0]
	v_pk_fma_f32 v[22:23], v[94:95], v[104:105], v[22:23] op_sel_hi:[0,1,1]
	v_pk_fma_f32 v[18:19], v[94:95], v[104:105], v[18:19] op_sel:[1,0,0]
	v_pk_fma_f32 v[36:37], v[92:93], v[106:107], v[36:37] op_sel_hi:[0,1,1]
	v_pk_fma_f32 v[28:29], v[92:93], v[106:107], v[28:29] op_sel:[1,0,0]
	v_pk_fma_f32 v[20:21], v[94:95], v[106:107], v[20:21] op_sel_hi:[0,1,1]
	v_pk_fma_f32 v[16:17], v[94:95], v[106:107], v[16:17] op_sel:[1,0,0]
	ds_read_b128 v[92:95], v87 offset:768
	s_waitcnt vmcnt(20) lgkmcnt(1)
	v_cvt_pk_f32_fp8_e32 v[100:101], v72
	v_cvt_pk_f32_fp8_sdwa v[102:103], v72 src0_sel:WORD_1
	v_cvt_pk_f32_fp8_e32 v[104:105], v73
	v_cvt_pk_f32_fp8_sdwa v[106:107], v73 src0_sel:WORD_1
	v_pk_fma_f32 v[48:49], v[96:97], v[100:101], v[48:49] op_sel_hi:[0,1,1]
	v_pk_fma_f32 v[44:45], v[96:97], v[100:101], v[44:45] op_sel:[1,0,0]
	v_pk_fma_f32 v[38:39], v[98:99], v[100:101], v[38:39] op_sel_hi:[0,1,1]
	v_pk_fma_f32 v[30:31], v[98:99], v[100:101], v[30:31] op_sel:[1,0,0]
	v_pk_fma_f32 v[46:47], v[96:97], v[102:103], v[46:47] op_sel_hi:[0,1,1]
	v_pk_fma_f32 v[42:43], v[96:97], v[102:103], v[42:43] op_sel:[1,0,0]
	v_pk_fma_f32 v[34:35], v[98:99], v[102:103], v[34:35] op_sel_hi:[0,1,1]
	v_pk_fma_f32 v[26:27], v[98:99], v[102:103], v[26:27] op_sel:[1,0,0]
	v_pk_fma_f32 v[40:41], v[96:97], v[104:105], v[40:41] op_sel_hi:[0,1,1]
	v_pk_fma_f32 v[32:33], v[96:97], v[104:105], v[32:33] op_sel:[1,0,0]
	v_pk_fma_f32 v[22:23], v[98:99], v[104:105], v[22:23] op_sel_hi:[0,1,1]
	v_pk_fma_f32 v[18:19], v[98:99], v[104:105], v[18:19] op_sel:[1,0,0]
	v_pk_fma_f32 v[36:37], v[96:97], v[106:107], v[36:37] op_sel_hi:[0,1,1]
	v_pk_fma_f32 v[28:29], v[96:97], v[106:107], v[28:29] op_sel:[1,0,0]
	v_pk_fma_f32 v[20:21], v[98:99], v[106:107], v[20:21] op_sel_hi:[0,1,1]
	v_pk_fma_f32 v[16:17], v[98:99], v[106:107], v[16:17] op_sel:[1,0,0]
	ds_read_b128 v[96:99], v87 offset:832
	s_waitcnt vmcnt(19) lgkmcnt(1)
	v_cvt_pk_f32_fp8_e32 v[100:101], v74
	v_cvt_pk_f32_fp8_sdwa v[102:103], v74 src0_sel:WORD_1
	v_cvt_pk_f32_fp8_e32 v[104:105], v75
	v_cvt_pk_f32_fp8_sdwa v[106:107], v75 src0_sel:WORD_1
	v_pk_fma_f32 v[48:49], v[92:93], v[100:101], v[48:49] op_sel_hi:[0,1,1]
	v_pk_fma_f32 v[44:45], v[92:93], v[100:101], v[44:45] op_sel:[1,0,0]
	v_pk_fma_f32 v[38:39], v[94:95], v[100:101], v[38:39] op_sel_hi:[0,1,1]
	v_pk_fma_f32 v[30:31], v[94:95], v[100:101], v[30:31] op_sel:[1,0,0]
	v_pk_fma_f32 v[46:47], v[92:93], v[102:103], v[46:47] op_sel_hi:[0,1,1]
	v_pk_fma_f32 v[42:43], v[92:93], v[102:103], v[42:43] op_sel:[1,0,0]
	v_pk_fma_f32 v[34:35], v[94:95], v[102:103], v[34:35] op_sel_hi:[0,1,1]
	v_pk_fma_f32 v[26:27], v[94:95], v[102:103], v[26:27] op_sel:[1,0,0]
	v_pk_fma_f32 v[40:41], v[92:93], v[104:105], v[40:41] op_sel_hi:[0,1,1]
	v_pk_fma_f32 v[32:33], v[92:93], v[104:105], v[32:33] op_sel:[1,0,0]
	v_pk_fma_f32 v[22:23], v[94:95], v[104:105], v[22:23] op_sel_hi:[0,1,1]
	v_pk_fma_f32 v[18:19], v[94:95], v[104:105], v[18:19] op_sel:[1,0,0]
	v_pk_fma_f32 v[36:37], v[92:93], v[106:107], v[36:37] op_sel_hi:[0,1,1]
	v_pk_fma_f32 v[28:29], v[92:93], v[106:107], v[28:29] op_sel:[1,0,0]
	v_pk_fma_f32 v[20:21], v[94:95], v[106:107], v[20:21] op_sel_hi:[0,1,1]
	v_pk_fma_f32 v[16:17], v[94:95], v[106:107], v[16:17] op_sel:[1,0,0]
	ds_read_b128 v[92:95], v87 offset:896
	s_waitcnt vmcnt(18) lgkmcnt(1)
; DI void attn_item(const P& p, int b, int kvh, int quad4, char* smem, const AttnPre& pre) {
;     ...
;     for (int u = 0; u < 16; ++u) vv[u] = *(const uint2*)(vb + (size_t)idx[n0 + 4 * u + quad] * 256);
; #pragma unroll
;     for (int u = 0; u < 16; ++u) {
;       const float4 p4 = *(const float4*)(L + (n0 + 4 * u + quad) * 4);
;       const f32x2_t c0 = __builtin_amdgcn_cvt_pk_f32_fp8((int)vv[u].x, false), c1 = __builtin_amdgcn_cvt_pk_f32_fp8((int)vv[u].x, true);
;       const f32x2_t c2 = __builtin_amdgcn_cvt_pk_f32_fp8((int)vv[u].y, false), c3 = __builtin_amdgcn_cvt_pk_f32_fp8((int)vv[u].y, true);
;       const float vf[8] = {c0.x, c0.y, c1.x, c1.y, c2.x, c2.y, c3.x, c3.y};
; #pragma unroll
;       for (int e = 0; e < 8; ++e) {
;         o[0][e] = fmaf(p4.x, vf[e], o[0][e]); o[1][e] = fmaf(p4.y, vf[e], o[1][e]);
;         o[2][e] = fmaf(p4.z, vf[e], o[2][e]); o[3][e] = fmaf(p4.w, vf[e], o[3][e]);
;       }
	v_cvt_pk_f32_fp8_e32 v[100:101], v76
	v_cvt_pk_f32_fp8_sdwa v[102:103], v76 src0_sel:WORD_1
	v_cvt_pk_f32_fp8_e32 v[104:105], v77
	v_cvt_pk_f32_fp8_sdwa v[106:107], v77 src0_sel:WORD_1
	v_pk_fma_f32 v[48:49], v[96:97], v[100:101], v[48:49] op_sel_hi:[0,1,1]
	v_pk_fma_f32 v[44:45], v[96:97], v[100:101], v[44:45] op_sel:[1,0,0]
	v_pk_fma_f32 v[38:39], v[98:99], v[100:101], v[38:39] op_sel_hi:[0,1,1]
	v_pk_fma_f32 v[30:31], v[98:99], v[100:101], v[30:31] op_sel:[1,0,0]
	v_pk_fma_f32 v[46:47], v[96:97], v[102:103], v[46:47] op_sel_hi:[0,1,1]
	v_pk_fma_f32 v[42:43], v[96:97], v[102:103], v[42:43] op_sel:[1,0,0]
	v_pk_fma_f32 v[34:35], v[98:99], v[102:103], v[34:35] op_sel_hi:[0,1,1]
	v_pk_fma_f32 v[26:27], v[98:99], v[102:103], v[26:27] op_sel:[1,0,0]
	v_pk_fma_f32 v[40:41], v[96:97], v[104:105], v[40:41] op_sel_hi:[0,1,1]
	v_pk_fma_f32 v[32:33], v[96:97], v[104:105], v[32:33] op_sel:[1,0,0]
	v_pk_fma_f32 v[22:23], v[98:99], v[104:105], v[22:23] op_sel_hi:[0,1,1]
	v_pk_fma_f32 v[18:19], v[98:99], v[104:105], v[18:19] op_sel:[1,0,0]
	v_pk_fma_f32 v[36:37], v[96:97], v[106:107], v[36:37] op_sel_hi:[0,1,1]
	v_pk_fma_f32 v[28:29], v[96:97], v[106:107], v[28:29] op_sel:[1,0,0]
	v_pk_fma_f32 v[20:21], v[98:99], v[106:107], v[20:21] op_sel_hi:[0,1,1]
	v_pk_fma_f32 v[16:17], v[98:99], v[106:107], v[16:17] op_sel:[1,0,0]
	ds_read_b128 v[96:99], v87 offset:960
	s_waitcnt vmcnt(17) lgkmcnt(1)
	v_cvt_pk_f32_fp8_e32 v[100:101], v78
	v_cvt_pk_f32_fp8_sdwa v[102:103], v78 src0_sel:WORD_1
	v_cvt_pk_f32_fp8_e32 v[104:105], v79
	v_cvt_pk_f32_fp8_sdwa v[106:107], v79 src0_sel:WORD_1
	v_pk_fma_f32 v[48:49], v[92:93], v[100:101], v[48:49] op_sel_hi:[0,1,1]
	v_pk_fma_f32 v[44:45], v[92:93], v[100:101], v[44:45] op_sel:[1,0,0]
	v_pk_fma_f32 v[38:39], v[94:95], v[100:101], v[38:39] op_sel_hi:[0,1,1]
	v_pk_fma_f32 v[30:31], v[94:95], v[100:101], v[30:31] op_sel:[1,0,0]
	v_pk_fma_f32 v[46:47], v[92:93], v[102:103], v[46:47] op_sel_hi:[0,1,1]
	v_pk_fma_f32 v[42:43], v[92:93], v[102:103], v[42:43] op_sel:[1,0,0]
	v_pk_fma_f32 v[34:35], v[94:95], v[102:103], v[34:35] op_sel_hi:[0,1,1]
	v_pk_fma_f32 v[26:27], v[94:95], v[102:103], v[26:27] op_sel:[1,0,0]
	v_pk_fma_f32 v[40:41], v[92:93], v[104:105], v[40:41] op_sel_hi:[0,1,1]
	v_pk_fma_f32 v[32:33], v[92:93], v[104:105], v[32:33] op_sel:[1,0,0]
	v_pk_fma_f32 v[22:23], v[94:95], v[104:105], v[22:23] op_sel_hi:[0,1,1]
	v_pk_fma_f32 v[18:19], v[94:95], v[104:105], v[18:19] op_sel:[1,0,0]
	v_pk_fma_f32 v[36:37], v[92:93], v[106:107], v[36:37] op_sel_hi:[0,1,1]
	v_pk_fma_f32 v[28:29], v[92:93], v[106:107], v[28:29] op_sel:[1,0,0]
	v_pk_fma_f32 v[20:21], v[94:95], v[106:107], v[20:21] op_sel_hi:[0,1,1]
	v_pk_fma_f32 v[16:17], v[94:95], v[106:107], v[16:17] op_sel:[1,0,0]
	ds_read_b128 v[92:95], v87 offset:1024
	s_waitcnt vmcnt(16) lgkmcnt(1)
	v_cvt_pk_f32_fp8_e32 v[100:101], v80
	v_cvt_pk_f32_fp8_sdwa v[102:103], v80 src0_sel:WORD_1
	v_cvt_pk_f32_fp8_e32 v[104:105], v81
	v_cvt_pk_f32_fp8_sdwa v[106:107], v81 src0_sel:WORD_1
	v_pk_fma_f32 v[48:49], v[96:97], v[100:101], v[48:49] op_sel_hi:[0,1,1]
	v_pk_fma_f32 v[44:45], v[96:97], v[100:101], v[44:45] op_sel:[1,0,0]
	v_pk_fma_f32 v[38:39], v[98:99], v[100:101], v[38:39] op_sel_hi:[0,1,1]
	v_pk_fma_f32 v[30:31], v[98:99], v[100:101], v[30:31] op_sel:[1,0,0]
	v_pk_fma_f32 v[46:47], v[96:97], v[102:103], v[46:47] op_sel_hi:[0,1,1]
	v_pk_fma_f32 v[42:43], v[96:97], v[102:103], v[42:43] op_sel:[1,0,0]
	v_pk_fma_f32 v[34:35], v[98:99], v[102:103], v[34:35] op_sel_hi:[0,1,1]
	v_pk_fma_f32 v[26:27], v[98:99], v[102:103], v[26:27] op_sel:[1,0,0]
	v_pk_fma_f32 v[40:41], v[96:97], v[104:105], v[40:41] op_sel_hi:[0,1,1]
	v_pk_fma_f32 v[32:33], v[96:97], v[104:105], v[32:33] op_sel:[1,0,0]
	v_pk_fma_f32 v[22:23], v[98:99], v[104:105], v[22:23] op_sel_hi:[0,1,1]
	v_pk_fma_f32 v[18:19], v[98:99], v[104:105], v[18:19] op_sel:[1,0,0]
	v_pk_fma_f32 v[36:37], v[96:97], v[106:107], v[36:37] op_sel_hi:[0,1,1]
	v_pk_fma_f32 v[28:29], v[96:97], v[106:107], v[28:29] op_sel:[1,0,0]
	v_pk_fma_f32 v[20:21], v[98:99], v[106:107], v[20:21] op_sel_hi:[0,1,1]
	v_pk_fma_f32 v[16:17], v[98:99], v[106:107], v[16:17] op_sel:[1,0,0]
	ds_read2_b32 v[152:153], v86 offset0:128 offset1:132
	ds_read2_b32 v[154:155], v86 offset0:136 offset1:140
	ds_read2_b32 v[156:157], v86 offset0:144 offset1:148
	ds_read2_b32 v[158:159], v86 offset0:152 offset1:156
	ds_read2_b32 v[160:161], v86 offset0:160 offset1:164
	ds_read2_b32 v[162:163], v86 offset0:168 offset1:172
	ds_read2_b32 v[164:165], v86 offset0:176 offset1:180
	ds_read2_b32 v[166:167], v86 offset0:184 offset1:188
	s_waitcnt lgkmcnt(0)
	v_lshl_add_u32 v152, v152, 8, v168
	v_lshl_add_u32 v153, v153, 8, v168
	v_lshl_add_u32 v154, v154, 8, v168
	v_lshl_add_u32 v155, v155, 8, v168
	v_lshl_add_u32 v156, v156, 8, v168
	v_lshl_add_u32 v157, v157, 8, v168
	v_lshl_add_u32 v158, v158, 8, v168
	v_lshl_add_u32 v159, v159, 8, v168
	v_lshl_add_u32 v160, v160, 8, v168
	v_lshl_add_u32 v161, v161, 8, v168
	v_lshl_add_u32 v162, v162, 8, v168
	v_lshl_add_u32 v163, v163, 8, v168
	v_lshl_add_u32 v164, v164, 8, v168
	v_lshl_add_u32 v165, v165, 8, v168
	v_lshl_add_u32 v166, v166, 8, v168
	v_lshl_add_u32 v167, v167, 8, v168
	global_load_dwordx2 v[50:51], v152, s[6:7]
	global_load_dwordx2 v[52:53], v153, s[6:7]
	global_load_dwordx2 v[54:55], v154, s[6:7]
	global_load_dwordx2 v[56:57], v155, s[6:7]
	global_load_dwordx2 v[58:59], v156, s[6:7]
	global_load_dwordx2 v[60:61], v157, s[6:7]
	global_load_dwordx2 v[62:63], v158, s[6:7]
	global_load_dwordx2 v[64:65], v159, s[6:7]
	global_load_dwordx2 v[66:67], v160, s[6:7]
	global_load_dwordx2 v[68:69], v161, s[6:7]
	global_load_dwordx2 v[70:71], v162, s[6:7]
	global_load_dwordx2 v[72:73], v163, s[6:7]
	global_load_dwordx2 v[74:75], v164, s[6:7]
	global_load_dwordx2 v[76:77], v165, s[6:7]
	global_load_dwordx2 v[78:79], v166, s[6:7]
	global_load_dwordx2 v[80:81], v167, s[6:7]
	ds_read_b128 v[96:99], v87 offset:1088
	s_waitcnt vmcnt(31) lgkmcnt(1)
; DI void attn_item(const P& p, int b, int kvh, int quad4, char* smem, const AttnPre& pre) {
;     ...
;     for (int u = 0; u < 16; ++u) vv[u] = *(const uint2*)(vb + (size_t)idx[n0 + 4 * u + quad] * 256);
; #pragma unroll
;     for (int u = 0; u < 16; ++u) {
;       const float4 p4 = *(const float4*)(L + (n0 + 4 * u + quad) * 4);
;       const f32x2_t c0 = __builtin_amdgcn_cvt_pk_f32_fp8((int)vv[u].x, false), c1 = __builtin_amdgcn_cvt_pk_f32_fp8((int)vv[u].x, true);
;       const f32x2_t c2 = __builtin_amdgcn_cvt_pk_f32_fp8((int)vv[u].y, false), c3 = __builtin_amdgcn_cvt_pk_f32_fp8((int)vv[u].y, true);
;       const float vf[8] = {c0.x, c0.y, c1.x, c1.y, c2.x, c2.y, c3.x, c3.y};
; #pragma unroll
;       for (int e = 0; e < 8; ++e) {
;         o[0][e] = fmaf(p4.x, vf[e], o[0][e]); o[1][e] = fmaf(p4.y, vf[e], o[1][e]);
;         o[2][e] = fmaf(p4.z, vf[e], o[2][e]); o[3][e] = fmaf(p4.w, vf[e], o[3][e]);
;       }
	v_cvt_pk_f32_fp8_e32 v[100:101], v120
	v_cvt_pk_f32_fp8_sdwa v[102:103], v120 src0_sel:WORD_1
	v_cvt_pk_f32_fp8_e32 v[104:105], v121
	v_cvt_pk_f32_fp8_sdwa v[106:107], v121 src0_sel:WORD_1
	v_pk_fma_f32 v[48:49], v[92:93], v[100:101], v[48:49] op_sel_hi:[0,1,1]
	v_pk_fma_f32 v[44:45], v[92:93], v[100:101], v[44:45] op_sel:[1,0,0]
	v_pk_fma_f32 v[38:39], v[94:95], v[100:101], v[38:39] op_sel_hi:[0,1,1]
	v_pk_fma_f32 v[30:31], v[94:95], v[100:101], v[30:31] op_sel:[1,0,0]
	v_pk_fma_f32 v[46:47], v[92:93], v[102:103], v[46:47] op_sel_hi:[0,1,1]
	v_pk_fma_f32 v[42:43], v[92:93], v[102:103], v[42:43] op_sel:[1,0,0]
	v_pk_fma_f32 v[34:35], v[94:95], v[102:103], v[34:35] op_sel_hi:[0,1,1]
	v_pk_fma_f32 v[26:27], v[94:95], v[102:103], v[26:27] op_sel:[1,0,0]
	v_pk_fma_f32 v[40:41], v[92:93], v[104:105], v[40:41] op_sel_hi:[0,1,1]
	v_pk_fma_f32 v[32:33], v[92:93], v[104:105], v[32:33] op_sel:[1,0,0]
	v_pk_fma_f32 v[22:23], v[94:95], v[104:105], v[22:23] op_sel_hi:[0,1,1]
	v_pk_fma_f32 v[18:19], v[94:95], v[104:105], v[18:19] op_sel:[1,0,0]
	v_pk_fma_f32 v[36:37], v[92:93], v[106:107], v[36:37] op_sel_hi:[0,1,1]
	v_pk_fma_f32 v[28:29], v[92:93], v[106:107], v[28:29] op_sel:[1,0,0]
	v_pk_fma_f32 v[20:21], v[94:95], v[106:107], v[20:21] op_sel_hi:[0,1,1]
	v_pk_fma_f32 v[16:17], v[94:95], v[106:107], v[16:17] op_sel:[1,0,0]
	ds_read_b128 v[92:95], v87 offset:1152
	s_waitcnt vmcnt(30) lgkmcnt(1)
	v_cvt_pk_f32_fp8_e32 v[100:101], v122
	v_cvt_pk_f32_fp8_sdwa v[102:103], v122 src0_sel:WORD_1
	v_cvt_pk_f32_fp8_e32 v[104:105], v123
	v_cvt_pk_f32_fp8_sdwa v[106:107], v123 src0_sel:WORD_1
	v_pk_fma_f32 v[48:49], v[96:97], v[100:101], v[48:49] op_sel_hi:[0,1,1]
	v_pk_fma_f32 v[44:45], v[96:97], v[100:101], v[44:45] op_sel:[1,0,0]
	v_pk_fma_f32 v[38:39], v[98:99], v[100:101], v[38:39] op_sel_hi:[0,1,1]
	v_pk_fma_f32 v[30:31], v[98:99], v[100:101], v[30:31] op_sel:[1,0,0]
	v_pk_fma_f32 v[46:47], v[96:97], v[102:103], v[46:47] op_sel_hi:[0,1,1]
	v_pk_fma_f32 v[42:43], v[96:97], v[102:103], v[42:43] op_sel:[1,0,0]
	v_pk_fma_f32 v[34:35], v[98:99], v[102:103], v[34:35] op_sel_hi:[0,1,1]
	v_pk_fma_f32 v[26:27], v[98:99], v[102:103], v[26:27] op_sel:[1,0,0]
	v_pk_fma_f32 v[40:41], v[96:97], v[104:105], v[40:41] op_sel_hi:[0,1,1]
	v_pk_fma_f32 v[32:33], v[96:97], v[104:105], v[32:33] op_sel:[1,0,0]
	v_pk_fma_f32 v[22:23], v[98:99], v[104:105], v[22:23] op_sel_hi:[0,1,1]
	v_pk_fma_f32 v[18:19], v[98:99], v[104:105], v[18:19] op_sel:[1,0,0]
	v_pk_fma_f32 v[36:37], v[96:97], v[106:107], v[36:37] op_sel_hi:[0,1,1]
	v_pk_fma_f32 v[28:29], v[96:97], v[106:107], v[28:29] op_sel:[1,0,0]
	v_pk_fma_f32 v[20:21], v[98:99], v[106:107], v[20:21] op_sel_hi:[0,1,1]
	v_pk_fma_f32 v[16:17], v[98:99], v[106:107], v[16:17] op_sel:[1,0,0]
	ds_read_b128 v[96:99], v87 offset:1216
	s_waitcnt vmcnt(29) lgkmcnt(1)
	v_cvt_pk_f32_fp8_e32 v[100:101], v124
	v_cvt_pk_f32_fp8_sdwa v[102:103], v124 src0_sel:WORD_1
	v_cvt_pk_f32_fp8_e32 v[104:105], v125
	v_cvt_pk_f32_fp8_sdwa v[106:107], v125 src0_sel:WORD_1
	v_pk_fma_f32 v[48:49], v[92:93], v[100:101], v[48:49] op_sel_hi:[0,1,1]
	v_pk_fma_f32 v[44:45], v[92:93], v[100:101], v[44:45] op_sel:[1,0,0]
	v_pk_fma_f32 v[38:39], v[94:95], v[100:101], v[38:39] op_sel_hi:[0,1,1]
	v_pk_fma_f32 v[30:31], v[94:95], v[100:101], v[30:31] op_sel:[1,0,0]
	v_pk_fma_f32 v[46:47], v[92:93], v[102:103], v[46:47] op_sel_hi:[0,1,1]
	v_pk_fma_f32 v[42:43], v[92:93], v[102:103], v[42:43] op_sel:[1,0,0]
	v_pk_fma_f32 v[34:35], v[94:95], v[102:103], v[34:35] op_sel_hi:[0,1,1]
	v_pk_fma_f32 v[26:27], v[94:95], v[102:103], v[26:27] op_sel:[1,0,0]
	v_pk_fma_f32 v[40:41], v[92:93], v[104:105], v[40:41] op_sel_hi:[0,1,1]
	v_pk_fma_f32 v[32:33], v[92:93], v[104:105], v[32:33] op_sel:[1,0,0]
	v_pk_fma_f32 v[22:23], v[94:95], v[104:105], v[22:23] op_sel_hi:[0,1,1]
	v_pk_fma_f32 v[18:19], v[94:95], v[104:105], v[18:19] op_sel:[1,0,0]
	v_pk_fma_f32 v[36:37], v[92:93], v[106:107], v[36:37] op_sel_hi:[0,1,1]
	v_pk_fma_f32 v[28:29], v[92:93], v[106:107], v[28:29] op_sel:[1,0,0]
	v_pk_fma_f32 v[20:21], v[94:95], v[106:107], v[20:21] op_sel_hi:[0,1,1]
	v_pk_fma_f32 v[16:17], v[94:95], v[106:107], v[16:17] op_sel:[1,0,0]
	ds_read_b128 v[92:95], v87 offset:1280
	s_waitcnt vmcnt(28) lgkmcnt(1)
	v_cvt_pk_f32_fp8_e32 v[100:101], v126
	v_cvt_pk_f32_fp8_sdwa v[102:103], v126 src0_sel:WORD_1
	v_cvt_pk_f32_fp8_e32 v[104:105], v127
	v_cvt_pk_f32_fp8_sdwa v[106:107], v127 src0_sel:WORD_1
	v_pk_fma_f32 v[48:49], v[96:97], v[100:101], v[48:49] op_sel_hi:[0,1,1]
	v_pk_fma_f32 v[44:45], v[96:97], v[100:101], v[44:45] op_sel:[1,0,0]
	v_pk_fma_f32 v[38:39], v[98:99], v[100:101], v[38:39] op_sel_hi:[0,1,1]
	v_pk_fma_f32 v[30:31], v[98:99], v[100:101], v[30:31] op_sel:[1,0,0]
	v_pk_fma_f32 v[46:47], v[96:97], v[102:103], v[46:47] op_sel_hi:[0,1,1]
	v_pk_fma_f32 v[42:43], v[96:97], v[102:103], v[42:43] op_sel:[1,0,0]
	v_pk_fma_f32 v[34:35], v[98:99], v[102:103], v[34:35] op_sel_hi:[0,1,1]
	v_pk_fma_f32 v[26:27], v[98:99], v[102:103], v[26:27] op_sel:[1,0,0]
	v_pk_fma_f32 v[40:41], v[96:97], v[104:105], v[40:41] op_sel_hi:[0,1,1]
	v_pk_fma_f32 v[32:33], v[96:97], v[104:105], v[32:33] op_sel:[1,0,0]
	v_pk_fma_f32 v[22:23], v[98:99], v[104:105], v[22:23] op_sel_hi:[0,1,1]
	v_pk_fma_f32 v[18:19], v[98:99], v[104:105], v[18:19] op_sel:[1,0,0]
	v_pk_fma_f32 v[36:37], v[96:97], v[106:107], v[36:37] op_sel_hi:[0,1,1]
	v_pk_fma_f32 v[28:29], v[96:97], v[106:107], v[28:29] op_sel:[1,0,0]
	v_pk_fma_f32 v[20:21], v[98:99], v[106:107], v[20:21] op_sel_hi:[0,1,1]
	v_pk_fma_f32 v[16:17], v[98:99], v[106:107], v[16:17] op_sel:[1,0,0]
	ds_read_b128 v[96:99], v87 offset:1344
	s_waitcnt vmcnt(27) lgkmcnt(1)
; DI void attn_item(const P& p, int b, int kvh, int quad4, char* smem, const AttnPre& pre) {
;     ...
;     for (int u = 0; u < 16; ++u) vv[u] = *(const uint2*)(vb + (size_t)idx[n0 + 4 * u + quad] * 256);
; #pragma unroll
;     for (int u = 0; u < 16; ++u) {
;       const float4 p4 = *(const float4*)(L + (n0 + 4 * u + quad) * 4);
;       const f32x2_t c0 = __builtin_amdgcn_cvt_pk_f32_fp8((int)vv[u].x, false), c1 = __builtin_amdgcn_cvt_pk_f32_fp8((int)vv[u].x, true);
;       const f32x2_t c2 = __builtin_amdgcn_cvt_pk_f32_fp8((int)vv[u].y, false), c3 = __builtin_amdgcn_cvt_pk_f32_fp8((int)vv[u].y, true);
;       const float vf[8] = {c0.x, c0.y, c1.x, c1.y, c2.x, c2.y, c3.x, c3.y};
; #pragma unroll
;       for (int e = 0; e < 8; ++e) {
;         o[0][e] = fmaf(p4.x, vf[e], o[0][e]); o[1][e] = fmaf(p4.y, vf[e], o[1][e]);
;         o[2][e] = fmaf(p4.z, vf[e], o[2][e]); o[3][e] = fmaf(p4.w, vf[e], o[3][e]);
;       }
	v_cvt_pk_f32_fp8_e32 v[100:101], v128
	v_cvt_pk_f32_fp8_sdwa v[102:103], v128 src0_sel:WORD_1
	v_cvt_pk_f32_fp8_e32 v[104:105], v129
	v_cvt_pk_f32_fp8_sdwa v[106:107], v129 src0_sel:WORD_1
	v_pk_fma_f32 v[48:49], v[92:93], v[100:101], v[48:49] op_sel_hi:[0,1,1]
	v_pk_fma_f32 v[44:45], v[92:93], v[100:101], v[44:45] op_sel:[1,0,0]
	v_pk_fma_f32 v[38:39], v[94:95], v[100:101], v[38:39] op_sel_hi:[0,1,1]
	v_pk_fma_f32 v[30:31], v[94:95], v[100:101], v[30:31] op_sel:[1,0,0]
	v_pk_fma_f32 v[46:47], v[92:93], v[102:103], v[46:47] op_sel_hi:[0,1,1]
	v_pk_fma_f32 v[42:43], v[92:93], v[102:103], v[42:43] op_sel:[1,0,0]
	v_pk_fma_f32 v[34:35], v[94:95], v[102:103], v[34:35] op_sel_hi:[0,1,1]
	v_pk_fma_f32 v[26:27], v[94:95], v[102:103], v[26:27] op_sel:[1,0,0]
	v_pk_fma_f32 v[40:41], v[92:93], v[104:105], v[40:41] op_sel_hi:[0,1,1]
	v_pk_fma_f32 v[32:33], v[92:93], v[104:105], v[32:33] op_sel:[1,0,0]
	v_pk_fma_f32 v[22:23], v[94:95], v[104:105], v[22:23] op_sel_hi:[0,1,1]
	v_pk_fma_f32 v[18:19], v[94:95], v[104:105], v[18:19] op_sel:[1,0,0]
	v_pk_fma_f32 v[36:37], v[92:93], v[106:107], v[36:37] op_sel_hi:[0,1,1]
	v_pk_fma_f32 v[28:29], v[92:93], v[106:107], v[28:29] op_sel:[1,0,0]
	v_pk_fma_f32 v[20:21], v[94:95], v[106:107], v[20:21] op_sel_hi:[0,1,1]
	v_pk_fma_f32 v[16:17], v[94:95], v[106:107], v[16:17] op_sel:[1,0,0]
	ds_read_b128 v[92:95], v87 offset:1408
	s_waitcnt vmcnt(26) lgkmcnt(1)
	v_cvt_pk_f32_fp8_e32 v[100:101], v130
	v_cvt_pk_f32_fp8_sdwa v[102:103], v130 src0_sel:WORD_1
	v_cvt_pk_f32_fp8_e32 v[104:105], v131
	v_cvt_pk_f32_fp8_sdwa v[106:107], v131 src0_sel:WORD_1
	v_pk_fma_f32 v[48:49], v[96:97], v[100:101], v[48:49] op_sel_hi:[0,1,1]
	v_pk_fma_f32 v[44:45], v[96:97], v[100:101], v[44:45] op_sel:[1,0,0]
	v_pk_fma_f32 v[38:39], v[98:99], v[100:101], v[38:39] op_sel_hi:[0,1,1]
	v_pk_fma_f32 v[30:31], v[98:99], v[100:101], v[30:31] op_sel:[1,0,0]
	v_pk_fma_f32 v[46:47], v[96:97], v[102:103], v[46:47] op_sel_hi:[0,1,1]
	v_pk_fma_f32 v[42:43], v[96:97], v[102:103], v[42:43] op_sel:[1,0,0]
	v_pk_fma_f32 v[34:35], v[98:99], v[102:103], v[34:35] op_sel_hi:[0,1,1]
	v_pk_fma_f32 v[26:27], v[98:99], v[102:103], v[26:27] op_sel:[1,0,0]
	v_pk_fma_f32 v[40:41], v[96:97], v[104:105], v[40:41] op_sel_hi:[0,1,1]
	v_pk_fma_f32 v[32:33], v[96:97], v[104:105], v[32:33] op_sel:[1,0,0]
	v_pk_fma_f32 v[22:23], v[98:99], v[104:105], v[22:23] op_sel_hi:[0,1,1]
	v_pk_fma_f32 v[18:19], v[98:99], v[104:105], v[18:19] op_sel:[1,0,0]
	v_pk_fma_f32 v[36:37], v[96:97], v[106:107], v[36:37] op_sel_hi:[0,1,1]
	v_pk_fma_f32 v[28:29], v[96:97], v[106:107], v[28:29] op_sel:[1,0,0]
	v_pk_fma_f32 v[20:21], v[98:99], v[106:107], v[20:21] op_sel_hi:[0,1,1]
	v_pk_fma_f32 v[16:17], v[98:99], v[106:107], v[16:17] op_sel:[1,0,0]
	ds_read_b128 v[96:99], v87 offset:1472
	s_waitcnt vmcnt(25) lgkmcnt(1)
	v_cvt_pk_f32_fp8_e32 v[100:101], v132
	v_cvt_pk_f32_fp8_sdwa v[102:103], v132 src0_sel:WORD_1
	v_cvt_pk_f32_fp8_e32 v[104:105], v133
	v_cvt_pk_f32_fp8_sdwa v[106:107], v133 src0_sel:WORD_1
	v_pk_fma_f32 v[48:49], v[92:93], v[100:101], v[48:49] op_sel_hi:[0,1,1]
	v_pk_fma_f32 v[44:45], v[92:93], v[100:101], v[44:45] op_sel:[1,0,0]
	v_pk_fma_f32 v[38:39], v[94:95], v[100:101], v[38:39] op_sel_hi:[0,1,1]
	v_pk_fma_f32 v[30:31], v[94:95], v[100:101], v[30:31] op_sel:[1,0,0]
	v_pk_fma_f32 v[46:47], v[92:93], v[102:103], v[46:47] op_sel_hi:[0,1,1]
	v_pk_fma_f32 v[42:43], v[92:93], v[102:103], v[42:43] op_sel:[1,0,0]
	v_pk_fma_f32 v[34:35], v[94:95], v[102:103], v[34:35] op_sel_hi:[0,1,1]
	v_pk_fma_f32 v[26:27], v[94:95], v[102:103], v[26:27] op_sel:[1,0,0]
	v_pk_fma_f32 v[40:41], v[92:93], v[104:105], v[40:41] op_sel_hi:[0,1,1]
	v_pk_fma_f32 v[32:33], v[92:93], v[104:105], v[32:33] op_sel:[1,0,0]
	v_pk_fma_f32 v[22:23], v[94:95], v[104:105], v[22:23] op_sel_hi:[0,1,1]
	v_pk_fma_f32 v[18:19], v[94:95], v[104:105], v[18:19] op_sel:[1,0,0]
	v_pk_fma_f32 v[36:37], v[92:93], v[106:107], v[36:37] op_sel_hi:[0,1,1]
	v_pk_fma_f32 v[28:29], v[92:93], v[106:107], v[28:29] op_sel:[1,0,0]
	v_pk_fma_f32 v[20:21], v[94:95], v[106:107], v[20:21] op_sel_hi:[0,1,1]
	v_pk_fma_f32 v[16:17], v[94:95], v[106:107], v[16:17] op_sel:[1,0,0]
	ds_read_b128 v[92:95], v87 offset:1536
	s_waitcnt vmcnt(24) lgkmcnt(1)
	v_cvt_pk_f32_fp8_e32 v[100:101], v134
	v_cvt_pk_f32_fp8_sdwa v[102:103], v134 src0_sel:WORD_1
	v_cvt_pk_f32_fp8_e32 v[104:105], v135
	v_cvt_pk_f32_fp8_sdwa v[106:107], v135 src0_sel:WORD_1
	v_pk_fma_f32 v[48:49], v[96:97], v[100:101], v[48:49] op_sel_hi:[0,1,1]
	v_pk_fma_f32 v[44:45], v[96:97], v[100:101], v[44:45] op_sel:[1,0,0]
	v_pk_fma_f32 v[38:39], v[98:99], v[100:101], v[38:39] op_sel_hi:[0,1,1]
	v_pk_fma_f32 v[30:31], v[98:99], v[100:101], v[30:31] op_sel:[1,0,0]
	v_pk_fma_f32 v[46:47], v[96:97], v[102:103], v[46:47] op_sel_hi:[0,1,1]
	v_pk_fma_f32 v[42:43], v[96:97], v[102:103], v[42:43] op_sel:[1,0,0]
	v_pk_fma_f32 v[34:35], v[98:99], v[102:103], v[34:35] op_sel_hi:[0,1,1]
	v_pk_fma_f32 v[26:27], v[98:99], v[102:103], v[26:27] op_sel:[1,0,0]
	v_pk_fma_f32 v[40:41], v[96:97], v[104:105], v[40:41] op_sel_hi:[0,1,1]
	v_pk_fma_f32 v[32:33], v[96:97], v[104:105], v[32:33] op_sel:[1,0,0]
	v_pk_fma_f32 v[22:23], v[98:99], v[104:105], v[22:23] op_sel_hi:[0,1,1]
	v_pk_fma_f32 v[18:19], v[98:99], v[104:105], v[18:19] op_sel:[1,0,0]
	v_pk_fma_f32 v[36:37], v[96:97], v[106:107], v[36:37] op_sel_hi:[0,1,1]
	v_pk_fma_f32 v[28:29], v[96:97], v[106:107], v[28:29] op_sel:[1,0,0]
	v_pk_fma_f32 v[20:21], v[98:99], v[106:107], v[20:21] op_sel_hi:[0,1,1]
	v_pk_fma_f32 v[16:17], v[98:99], v[106:107], v[16:17] op_sel:[1,0,0]
	ds_read_b128 v[96:99], v87 offset:1600
	s_waitcnt vmcnt(23) lgkmcnt(1)
; DI void attn_item(const P& p, int b, int kvh, int quad4, char* smem, const AttnPre& pre) {
;     ...
;     for (int u = 0; u < 16; ++u) vv[u] = *(const uint2*)(vb + (size_t)idx[n0 + 4 * u + quad] * 256);
; #pragma unroll
;     for (int u = 0; u < 16; ++u) {
;       const float4 p4 = *(const float4*)(L + (n0 + 4 * u + quad) * 4);
;       const f32x2_t c0 = __builtin_amdgcn_cvt_pk_f32_fp8((int)vv[u].x, false), c1 = __builtin_amdgcn_cvt_pk_f32_fp8((int)vv[u].x, true);
;       const f32x2_t c2 = __builtin_amdgcn_cvt_pk_f32_fp8((int)vv[u].y, false), c3 = __builtin_amdgcn_cvt_pk_f32_fp8((int)vv[u].y, true);
;       const float vf[8] = {c0.x, c0.y, c1.x, c1.y, c2.x, c2.y, c3.x, c3.y};
; #pragma unroll
;       for (int e = 0; e < 8; ++e) {
;         o[0][e] = fmaf(p4.x, vf[e], o[0][e]); o[1][e] = fmaf(p4.y, vf[e], o[1][e]);
;         o[2][e] = fmaf(p4.z, vf[e], o[2][e]); o[3][e] = fmaf(p4.w, vf[e], o[3][e]);
;       }
	v_cvt_pk_f32_fp8_e32 v[100:101], v136
	v_cvt_pk_f32_fp8_sdwa v[102:103], v136 src0_sel:WORD_1
	v_cvt_pk_f32_fp8_e32 v[104:105], v137
	v_cvt_pk_f32_fp8_sdwa v[106:107], v137 src0_sel:WORD_1
	v_pk_fma_f32 v[48:49], v[92:93], v[100:101], v[48:49] op_sel_hi:[0,1,1]
	v_pk_fma_f32 v[44:45], v[92:93], v[100:101], v[44:45] op_sel:[1,0,0]
	v_pk_fma_f32 v[38:39], v[94:95], v[100:101], v[38:39] op_sel_hi:[0,1,1]
	v_pk_fma_f32 v[30:31], v[94:95], v[100:101], v[30:31] op_sel:[1,0,0]
	v_pk_fma_f32 v[46:47], v[92:93], v[102:103], v[46:47] op_sel_hi:[0,1,1]
	v_pk_fma_f32 v[42:43], v[92:93], v[102:103], v[42:43] op_sel:[1,0,0]
	v_pk_fma_f32 v[34:35], v[94:95], v[102:103], v[34:35] op_sel_hi:[0,1,1]
	v_pk_fma_f32 v[26:27], v[94:95], v[102:103], v[26:27] op_sel:[1,0,0]
	v_pk_fma_f32 v[40:41], v[92:93], v[104:105], v[40:41] op_sel_hi:[0,1,1]
	v_pk_fma_f32 v[32:33], v[92:93], v[104:105], v[32:33] op_sel:[1,0,0]
	v_pk_fma_f32 v[22:23], v[94:95], v[104:105], v[22:23] op_sel_hi:[0,1,1]
	v_pk_fma_f32 v[18:19], v[94:95], v[104:105], v[18:19] op_sel:[1,0,0]
	v_pk_fma_f32 v[36:37], v[92:93], v[106:107], v[36:37] op_sel_hi:[0,1,1]
	v_pk_fma_f32 v[28:29], v[92:93], v[106:107], v[28:29] op_sel:[1,0,0]
	v_pk_fma_f32 v[20:21], v[94:95], v[106:107], v[20:21] op_sel_hi:[0,1,1]
	v_pk_fma_f32 v[16:17], v[94:95], v[106:107], v[16:17] op_sel:[1,0,0]
	ds_read_b128 v[92:95], v87 offset:1664
	s_waitcnt vmcnt(22) lgkmcnt(1)
	v_cvt_pk_f32_fp8_e32 v[100:101], v138
	v_cvt_pk_f32_fp8_sdwa v[102:103], v138 src0_sel:WORD_1
	v_cvt_pk_f32_fp8_e32 v[104:105], v139
	v_cvt_pk_f32_fp8_sdwa v[106:107], v139 src0_sel:WORD_1
	v_pk_fma_f32 v[48:49], v[96:97], v[100:101], v[48:49] op_sel_hi:[0,1,1]
	v_pk_fma_f32 v[44:45], v[96:97], v[100:101], v[44:45] op_sel:[1,0,0]
	v_pk_fma_f32 v[38:39], v[98:99], v[100:101], v[38:39] op_sel_hi:[0,1,1]
	v_pk_fma_f32 v[30:31], v[98:99], v[100:101], v[30:31] op_sel:[1,0,0]
	v_pk_fma_f32 v[46:47], v[96:97], v[102:103], v[46:47] op_sel_hi:[0,1,1]
	v_pk_fma_f32 v[42:43], v[96:97], v[102:103], v[42:43] op_sel:[1,0,0]
	v_pk_fma_f32 v[34:35], v[98:99], v[102:103], v[34:35] op_sel_hi:[0,1,1]
	v_pk_fma_f32 v[26:27], v[98:99], v[102:103], v[26:27] op_sel:[1,0,0]
	v_pk_fma_f32 v[40:41], v[96:97], v[104:105], v[40:41] op_sel_hi:[0,1,1]
	v_pk_fma_f32 v[32:33], v[96:97], v[104:105], v[32:33] op_sel:[1,0,0]
	v_pk_fma_f32 v[22:23], v[98:99], v[104:105], v[22:23] op_sel_hi:[0,1,1]
	v_pk_fma_f32 v[18:19], v[98:99], v[104:105], v[18:19] op_sel:[1,0,0]
	v_pk_fma_f32 v[36:37], v[96:97], v[106:107], v[36:37] op_sel_hi:[0,1,1]
	v_pk_fma_f32 v[28:29], v[96:97], v[106:107], v[28:29] op_sel:[1,0,0]
	v_pk_fma_f32 v[20:21], v[98:99], v[106:107], v[20:21] op_sel_hi:[0,1,1]
	v_pk_fma_f32 v[16:17], v[98:99], v[106:107], v[16:17] op_sel:[1,0,0]
	ds_read_b128 v[96:99], v87 offset:1728
	s_waitcnt vmcnt(21) lgkmcnt(1)
	v_cvt_pk_f32_fp8_e32 v[100:101], v140
	v_cvt_pk_f32_fp8_sdwa v[102:103], v140 src0_sel:WORD_1
	v_cvt_pk_f32_fp8_e32 v[104:105], v141
	v_cvt_pk_f32_fp8_sdwa v[106:107], v141 src0_sel:WORD_1
	v_pk_fma_f32 v[48:49], v[92:93], v[100:101], v[48:49] op_sel_hi:[0,1,1]
	v_pk_fma_f32 v[44:45], v[92:93], v[100:101], v[44:45] op_sel:[1,0,0]
	v_pk_fma_f32 v[38:39], v[94:95], v[100:101], v[38:39] op_sel_hi:[0,1,1]
	v_pk_fma_f32 v[30:31], v[94:95], v[100:101], v[30:31] op_sel:[1,0,0]
	v_pk_fma_f32 v[46:47], v[92:93], v[102:103], v[46:47] op_sel_hi:[0,1,1]
	v_pk_fma_f32 v[42:43], v[92:93], v[102:103], v[42:43] op_sel:[1,0,0]
	v_pk_fma_f32 v[34:35], v[94:95], v[102:103], v[34:35] op_sel_hi:[0,1,1]
	v_pk_fma_f32 v[26:27], v[94:95], v[102:103], v[26:27] op_sel:[1,0,0]
	v_pk_fma_f32 v[40:41], v[92:93], v[104:105], v[40:41] op_sel_hi:[0,1,1]
	v_pk_fma_f32 v[32:33], v[92:93], v[104:105], v[32:33] op_sel:[1,0,0]
	v_pk_fma_f32 v[22:23], v[94:95], v[104:105], v[22:23] op_sel_hi:[0,1,1]
	v_pk_fma_f32 v[18:19], v[94:95], v[104:105], v[18:19] op_sel:[1,0,0]
	v_pk_fma_f32 v[36:37], v[92:93], v[106:107], v[36:37] op_sel_hi:[0,1,1]
	v_pk_fma_f32 v[28:29], v[92:93], v[106:107], v[28:29] op_sel:[1,0,0]
	v_pk_fma_f32 v[20:21], v[94:95], v[106:107], v[20:21] op_sel_hi:[0,1,1]
	v_pk_fma_f32 v[16:17], v[94:95], v[106:107], v[16:17] op_sel:[1,0,0]
	ds_read_b128 v[92:95], v87 offset:1792
	s_waitcnt vmcnt(20) lgkmcnt(1)
	v_cvt_pk_f32_fp8_e32 v[100:101], v142
	v_cvt_pk_f32_fp8_sdwa v[102:103], v142 src0_sel:WORD_1
	v_cvt_pk_f32_fp8_e32 v[104:105], v143
	v_cvt_pk_f32_fp8_sdwa v[106:107], v143 src0_sel:WORD_1
	v_pk_fma_f32 v[48:49], v[96:97], v[100:101], v[48:49] op_sel_hi:[0,1,1]
	v_pk_fma_f32 v[44:45], v[96:97], v[100:101], v[44:45] op_sel:[1,0,0]
	v_pk_fma_f32 v[38:39], v[98:99], v[100:101], v[38:39] op_sel_hi:[0,1,1]
	v_pk_fma_f32 v[30:31], v[98:99], v[100:101], v[30:31] op_sel:[1,0,0]
	v_pk_fma_f32 v[46:47], v[96:97], v[102:103], v[46:47] op_sel_hi:[0,1,1]
	v_pk_fma_f32 v[42:43], v[96:97], v[102:103], v[42:43] op_sel:[1,0,0]
	v_pk_fma_f32 v[34:35], v[98:99], v[102:103], v[34:35] op_sel_hi:[0,1,1]
	v_pk_fma_f32 v[26:27], v[98:99], v[102:103], v[26:27] op_sel:[1,0,0]
	v_pk_fma_f32 v[40:41], v[96:97], v[104:105], v[40:41] op_sel_hi:[0,1,1]
	v_pk_fma_f32 v[32:33], v[96:97], v[104:105], v[32:33] op_sel:[1,0,0]
	v_pk_fma_f32 v[22:23], v[98:99], v[104:105], v[22:23] op_sel_hi:[0,1,1]
	v_pk_fma_f32 v[18:19], v[98:99], v[104:105], v[18:19] op_sel:[1,0,0]
	v_pk_fma_f32 v[36:37], v[96:97], v[106:107], v[36:37] op_sel_hi:[0,1,1]
	v_pk_fma_f32 v[28:29], v[96:97], v[106:107], v[28:29] op_sel:[1,0,0]
	v_pk_fma_f32 v[20:21], v[98:99], v[106:107], v[20:21] op_sel_hi:[0,1,1]
	v_pk_fma_f32 v[16:17], v[98:99], v[106:107], v[16:17] op_sel:[1,0,0]
	ds_read_b128 v[96:99], v87 offset:1856
	s_waitcnt vmcnt(19) lgkmcnt(1)
; DI void attn_item(const P& p, int b, int kvh, int quad4, char* smem, const AttnPre& pre) {
;     ...
;     for (int u = 0; u < 16; ++u) vv[u] = *(const uint2*)(vb + (size_t)idx[n0 + 4 * u + quad] * 256);
; #pragma unroll
;     for (int u = 0; u < 16; ++u) {
;       const float4 p4 = *(const float4*)(L + (n0 + 4 * u + quad) * 4);
;       const f32x2_t c0 = __builtin_amdgcn_cvt_pk_f32_fp8((int)vv[u].x, false), c1 = __builtin_amdgcn_cvt_pk_f32_fp8((int)vv[u].x, true);
;       const f32x2_t c2 = __builtin_amdgcn_cvt_pk_f32_fp8((int)vv[u].y, false), c3 = __builtin_amdgcn_cvt_pk_f32_fp8((int)vv[u].y, true);
;       const float vf[8] = {c0.x, c0.y, c1.x, c1.y, c2.x, c2.y, c3.x, c3.y};
; #pragma unroll
;       for (int e = 0; e < 8; ++e) {
;         o[0][e] = fmaf(p4.x, vf[e], o[0][e]); o[1][e] = fmaf(p4.y, vf[e], o[1][e]);
;         o[2][e] = fmaf(p4.z, vf[e], o[2][e]); o[3][e] = fmaf(p4.w, vf[e], o[3][e]);
;       }
	v_cvt_pk_f32_fp8_e32 v[100:101], v144
	v_cvt_pk_f32_fp8_sdwa v[102:103], v144 src0_sel:WORD_1
	v_cvt_pk_f32_fp8_e32 v[104:105], v145
	v_cvt_pk_f32_fp8_sdwa v[106:107], v145 src0_sel:WORD_1
	v_pk_fma_f32 v[48:49], v[92:93], v[100:101], v[48:49] op_sel_hi:[0,1,1]
	v_pk_fma_f32 v[44:45], v[92:93], v[100:101], v[44:45] op_sel:[1,0,0]
	v_pk_fma_f32 v[38:39], v[94:95], v[100:101], v[38:39] op_sel_hi:[0,1,1]
	v_pk_fma_f32 v[30:31], v[94:95], v[100:101], v[30:31] op_sel:[1,0,0]
	v_pk_fma_f32 v[46:47], v[92:93], v[102:103], v[46:47] op_sel_hi:[0,1,1]
	v_pk_fma_f32 v[42:43], v[92:93], v[102:103], v[42:43] op_sel:[1,0,0]
	v_pk_fma_f32 v[34:35], v[94:95], v[102:103], v[34:35] op_sel_hi:[0,1,1]
	v_pk_fma_f32 v[26:27], v[94:95], v[102:103], v[26:27] op_sel:[1,0,0]
	v_pk_fma_f32 v[40:41], v[92:93], v[104:105], v[40:41] op_sel_hi:[0,1,1]
	v_pk_fma_f32 v[32:33], v[92:93], v[104:105], v[32:33] op_sel:[1,0,0]
	v_pk_fma_f32 v[22:23], v[94:95], v[104:105], v[22:23] op_sel_hi:[0,1,1]
	v_pk_fma_f32 v[18:19], v[94:95], v[104:105], v[18:19] op_sel:[1,0,0]
	v_pk_fma_f32 v[36:37], v[92:93], v[106:107], v[36:37] op_sel_hi:[0,1,1]
	v_pk_fma_f32 v[28:29], v[92:93], v[106:107], v[28:29] op_sel:[1,0,0]
	v_pk_fma_f32 v[20:21], v[94:95], v[106:107], v[20:21] op_sel_hi:[0,1,1]
	v_pk_fma_f32 v[16:17], v[94:95], v[106:107], v[16:17] op_sel:[1,0,0]
	ds_read_b128 v[92:95], v87 offset:1920
	s_waitcnt vmcnt(18) lgkmcnt(1)
	v_cvt_pk_f32_fp8_e32 v[100:101], v146
	v_cvt_pk_f32_fp8_sdwa v[102:103], v146 src0_sel:WORD_1
	v_cvt_pk_f32_fp8_e32 v[104:105], v147
	v_cvt_pk_f32_fp8_sdwa v[106:107], v147 src0_sel:WORD_1
	v_pk_fma_f32 v[48:49], v[96:97], v[100:101], v[48:49] op_sel_hi:[0,1,1]
	v_pk_fma_f32 v[44:45], v[96:97], v[100:101], v[44:45] op_sel:[1,0,0]
	v_pk_fma_f32 v[38:39], v[98:99], v[100:101], v[38:39] op_sel_hi:[0,1,1]
	v_pk_fma_f32 v[30:31], v[98:99], v[100:101], v[30:31] op_sel:[1,0,0]
	v_pk_fma_f32 v[46:47], v[96:97], v[102:103], v[46:47] op_sel_hi:[0,1,1]
	v_pk_fma_f32 v[42:43], v[96:97], v[102:103], v[42:43] op_sel:[1,0,0]
	v_pk_fma_f32 v[34:35], v[98:99], v[102:103], v[34:35] op_sel_hi:[0,1,1]
	v_pk_fma_f32 v[26:27], v[98:99], v[102:103], v[26:27] op_sel:[1,0,0]
	v_pk_fma_f32 v[40:41], v[96:97], v[104:105], v[40:41] op_sel_hi:[0,1,1]
	v_pk_fma_f32 v[32:33], v[96:97], v[104:105], v[32:33] op_sel:[1,0,0]
	v_pk_fma_f32 v[22:23], v[98:99], v[104:105], v[22:23] op_sel_hi:[0,1,1]
	v_pk_fma_f32 v[18:19], v[98:99], v[104:105], v[18:19] op_sel:[1,0,0]
	v_pk_fma_f32 v[36:37], v[96:97], v[106:107], v[36:37] op_sel_hi:[0,1,1]
	v_pk_fma_f32 v[28:29], v[96:97], v[106:107], v[28:29] op_sel:[1,0,0]
	v_pk_fma_f32 v[20:21], v[98:99], v[106:107], v[20:21] op_sel_hi:[0,1,1]
	v_pk_fma_f32 v[16:17], v[98:99], v[106:107], v[16:17] op_sel:[1,0,0]
	ds_read_b128 v[96:99], v87 offset:1984
	s_waitcnt vmcnt(17) lgkmcnt(1)
	v_cvt_pk_f32_fp8_e32 v[100:101], v148
	v_cvt_pk_f32_fp8_sdwa v[102:103], v148 src0_sel:WORD_1
	v_cvt_pk_f32_fp8_e32 v[104:105], v149
	v_cvt_pk_f32_fp8_sdwa v[106:107], v149 src0_sel:WORD_1
	v_pk_fma_f32 v[48:49], v[92:93], v[100:101], v[48:49] op_sel_hi:[0,1,1]
	v_pk_fma_f32 v[44:45], v[92:93], v[100:101], v[44:45] op_sel:[1,0,0]
	v_pk_fma_f32 v[38:39], v[94:95], v[100:101], v[38:39] op_sel_hi:[0,1,1]
	v_pk_fma_f32 v[30:31], v[94:95], v[100:101], v[30:31] op_sel:[1,0,0]
	v_pk_fma_f32 v[46:47], v[92:93], v[102:103], v[46:47] op_sel_hi:[0,1,1]
	v_pk_fma_f32 v[42:43], v[92:93], v[102:103], v[42:43] op_sel:[1,0,0]
	v_pk_fma_f32 v[34:35], v[94:95], v[102:103], v[34:35] op_sel_hi:[0,1,1]
	v_pk_fma_f32 v[26:27], v[94:95], v[102:103], v[26:27] op_sel:[1,0,0]
	v_pk_fma_f32 v[40:41], v[92:93], v[104:105], v[40:41] op_sel_hi:[0,1,1]
	v_pk_fma_f32 v[32:33], v[92:93], v[104:105], v[32:33] op_sel:[1,0,0]
	v_pk_fma_f32 v[22:23], v[94:95], v[104:105], v[22:23] op_sel_hi:[0,1,1]
	v_pk_fma_f32 v[18:19], v[94:95], v[104:105], v[18:19] op_sel:[1,0,0]
	v_pk_fma_f32 v[36:37], v[92:93], v[106:107], v[36:37] op_sel_hi:[0,1,1]
	v_pk_fma_f32 v[28:29], v[92:93], v[106:107], v[28:29] op_sel:[1,0,0]
	v_pk_fma_f32 v[20:21], v[94:95], v[106:107], v[20:21] op_sel_hi:[0,1,1]
	v_pk_fma_f32 v[16:17], v[94:95], v[106:107], v[16:17] op_sel:[1,0,0]
	ds_read_b128 v[92:95], v87 offset:2048
	s_waitcnt vmcnt(16) lgkmcnt(1)
	v_cvt_pk_f32_fp8_e32 v[100:101], v150
	v_cvt_pk_f32_fp8_sdwa v[102:103], v150 src0_sel:WORD_1
	v_cvt_pk_f32_fp8_e32 v[104:105], v151
	v_cvt_pk_f32_fp8_sdwa v[106:107], v151 src0_sel:WORD_1
	v_pk_fma_f32 v[48:49], v[96:97], v[100:101], v[48:49] op_sel_hi:[0,1,1]
	v_pk_fma_f32 v[44:45], v[96:97], v[100:101], v[44:45] op_sel:[1,0,0]
	v_pk_fma_f32 v[38:39], v[98:99], v[100:101], v[38:39] op_sel_hi:[0,1,1]
	v_pk_fma_f32 v[30:31], v[98:99], v[100:101], v[30:31] op_sel:[1,0,0]
	v_pk_fma_f32 v[46:47], v[96:97], v[102:103], v[46:47] op_sel_hi:[0,1,1]
	v_pk_fma_f32 v[42:43], v[96:97], v[102:103], v[42:43] op_sel:[1,0,0]
	v_pk_fma_f32 v[34:35], v[98:99], v[102:103], v[34:35] op_sel_hi:[0,1,1]
	v_pk_fma_f32 v[26:27], v[98:99], v[102:103], v[26:27] op_sel:[1,0,0]
	v_pk_fma_f32 v[40:41], v[96:97], v[104:105], v[40:41] op_sel_hi:[0,1,1]
	v_pk_fma_f32 v[32:33], v[96:97], v[104:105], v[32:33] op_sel:[1,0,0]
	v_pk_fma_f32 v[22:23], v[98:99], v[104:105], v[22:23] op_sel_hi:[0,1,1]
	v_pk_fma_f32 v[18:19], v[98:99], v[104:105], v[18:19] op_sel:[1,0,0]
	v_pk_fma_f32 v[36:37], v[96:97], v[106:107], v[36:37] op_sel_hi:[0,1,1]
	v_pk_fma_f32 v[28:29], v[96:97], v[106:107], v[28:29] op_sel:[1,0,0]
	v_pk_fma_f32 v[20:21], v[98:99], v[106:107], v[20:21] op_sel_hi:[0,1,1]
	v_pk_fma_f32 v[16:17], v[98:99], v[106:107], v[16:17] op_sel:[1,0,0]
	ds_read2_b32 v[152:153], v86 offset0:192 offset1:196
	ds_read2_b32 v[154:155], v86 offset0:200 offset1:204
	ds_read2_b32 v[156:157], v86 offset0:208 offset1:212
	ds_read2_b32 v[158:159], v86 offset0:216 offset1:220
	ds_read2_b32 v[160:161], v86 offset0:224 offset1:228
	ds_read2_b32 v[162:163], v86 offset0:232 offset1:236
	ds_read2_b32 v[164:165], v86 offset0:240 offset1:244
	ds_read2_b32 v[166:167], v86 offset0:248 offset1:252
	s_waitcnt lgkmcnt(0)
; DI void attn_item(const P& p, int b, int kvh, int quad4, char* smem, const AttnPre& pre) {
;     ...
;     for (int u = 0; u < 16; ++u) vv[u] = *(const uint2*)(vb + (size_t)idx[n0 + 4 * u + quad] * 256);
; #pragma unroll
;     for (int u = 0; u < 16; ++u) {
;       const float4 p4 = *(const float4*)(L + (n0 + 4 * u + quad) * 4);
;       const f32x2_t c0 = __builtin_amdgcn_cvt_pk_f32_fp8((int)vv[u].x, false), c1 = __builtin_amdgcn_cvt_pk_f32_fp8((int)vv[u].x, true);
;       const f32x2_t c2 = __builtin_amdgcn_cvt_pk_f32_fp8((int)vv[u].y, false), c3 = __builtin_amdgcn_cvt_pk_f32_fp8((int)vv[u].y, true);
;       const float vf[8] = {c0.x, c0.y, c1.x, c1.y, c2.x, c2.y, c3.x, c3.y};
; #pragma unroll
;       for (int e = 0; e < 8; ++e) {
;         o[0][e] = fmaf(p4.x, vf[e], o[0][e]); o[1][e] = fmaf(p4.y, vf[e], o[1][e]);
;         o[2][e] = fmaf(p4.z, vf[e], o[2][e]); o[3][e] = fmaf(p4.w, vf[e], o[3][e]);
;       }
	v_lshl_add_u32 v152, v152, 8, v168
	v_lshl_add_u32 v153, v153, 8, v168
	v_lshl_add_u32 v154, v154, 8, v168
	v_lshl_add_u32 v155, v155, 8, v168
	v_lshl_add_u32 v156, v156, 8, v168
	v_lshl_add_u32 v157, v157, 8, v168
	v_lshl_add_u32 v158, v158, 8, v168
	v_lshl_add_u32 v159, v159, 8, v168
	v_lshl_add_u32 v160, v160, 8, v168
	v_lshl_add_u32 v161, v161, 8, v168
	v_lshl_add_u32 v162, v162, 8, v168
	v_lshl_add_u32 v163, v163, 8, v168
	v_lshl_add_u32 v164, v164, 8, v168
	v_lshl_add_u32 v165, v165, 8, v168
	v_lshl_add_u32 v166, v166, 8, v168
	v_lshl_add_u32 v167, v167, 8, v168
	global_load_dwordx2 v[120:121], v152, s[6:7]
	global_load_dwordx2 v[122:123], v153, s[6:7]
	global_load_dwordx2 v[124:125], v154, s[6:7]
	global_load_dwordx2 v[126:127], v155, s[6:7]
	global_load_dwordx2 v[128:129], v156, s[6:7]
	global_load_dwordx2 v[130:131], v157, s[6:7]
	global_load_dwordx2 v[132:133], v158, s[6:7]
	global_load_dwordx2 v[134:135], v159, s[6:7]
	global_load_dwordx2 v[136:137], v160, s[6:7]
	global_load_dwordx2 v[138:139], v161, s[6:7]
	global_load_dwordx2 v[140:141], v162, s[6:7]
	global_load_dwordx2 v[142:143], v163, s[6:7]
	global_load_dwordx2 v[144:145], v164, s[6:7]
	global_load_dwordx2 v[146:147], v165, s[6:7]
	global_load_dwordx2 v[148:149], v166, s[6:7]
	global_load_dwordx2 v[150:151], v167, s[6:7]
	ds_read_b128 v[96:99], v87 offset:2112
	s_waitcnt vmcnt(31) lgkmcnt(1)
	v_cvt_pk_f32_fp8_e32 v[100:101], v50
	v_cvt_pk_f32_fp8_sdwa v[102:103], v50 src0_sel:WORD_1
	v_cvt_pk_f32_fp8_e32 v[104:105], v51
	v_cvt_pk_f32_fp8_sdwa v[106:107], v51 src0_sel:WORD_1
	v_pk_fma_f32 v[48:49], v[92:93], v[100:101], v[48:49] op_sel_hi:[0,1,1]
	v_pk_fma_f32 v[44:45], v[92:93], v[100:101], v[44:45] op_sel:[1,0,0]
	v_pk_fma_f32 v[38:39], v[94:95], v[100:101], v[38:39] op_sel_hi:[0,1,1]
	v_pk_fma_f32 v[30:31], v[94:95], v[100:101], v[30:31] op_sel:[1,0,0]
	v_pk_fma_f32 v[46:47], v[92:93], v[102:103], v[46:47] op_sel_hi:[0,1,1]
	v_pk_fma_f32 v[42:43], v[92:93], v[102:103], v[42:43] op_sel:[1,0,0]
	v_pk_fma_f32 v[34:35], v[94:95], v[102:103], v[34:35] op_sel_hi:[0,1,1]
	v_pk_fma_f32 v[26:27], v[94:95], v[102:103], v[26:27] op_sel:[1,0,0]
	v_pk_fma_f32 v[40:41], v[92:93], v[104:105], v[40:41] op_sel_hi:[0,1,1]
	v_pk_fma_f32 v[32:33], v[92:93], v[104:105], v[32:33] op_sel:[1,0,0]
	v_pk_fma_f32 v[22:23], v[94:95], v[104:105], v[22:23] op_sel_hi:[0,1,1]
	v_pk_fma_f32 v[18:19], v[94:95], v[104:105], v[18:19] op_sel:[1,0,0]
	v_pk_fma_f32 v[36:37], v[92:93], v[106:107], v[36:37] op_sel_hi:[0,1,1]
	v_pk_fma_f32 v[28:29], v[92:93], v[106:107], v[28:29] op_sel:[1,0,0]
	v_pk_fma_f32 v[20:21], v[94:95], v[106:107], v[20:21] op_sel_hi:[0,1,1]
	v_pk_fma_f32 v[16:17], v[94:95], v[106:107], v[16:17] op_sel:[1,0,0]
	ds_read_b128 v[92:95], v87 offset:2176
	s_waitcnt vmcnt(30) lgkmcnt(1)
	v_cvt_pk_f32_fp8_e32 v[100:101], v52
	v_cvt_pk_f32_fp8_sdwa v[102:103], v52 src0_sel:WORD_1
	v_cvt_pk_f32_fp8_e32 v[104:105], v53
	v_cvt_pk_f32_fp8_sdwa v[106:107], v53 src0_sel:WORD_1
	v_pk_fma_f32 v[48:49], v[96:97], v[100:101], v[48:49] op_sel_hi:[0,1,1]
	v_pk_fma_f32 v[44:45], v[96:97], v[100:101], v[44:45] op_sel:[1,0,0]
	v_pk_fma_f32 v[38:39], v[98:99], v[100:101], v[38:39] op_sel_hi:[0,1,1]
	v_pk_fma_f32 v[30:31], v[98:99], v[100:101], v[30:31] op_sel:[1,0,0]
	v_pk_fma_f32 v[46:47], v[96:97], v[102:103], v[46:47] op_sel_hi:[0,1,1]
	v_pk_fma_f32 v[42:43], v[96:97], v[102:103], v[42:43] op_sel:[1,0,0]
	v_pk_fma_f32 v[34:35], v[98:99], v[102:103], v[34:35] op_sel_hi:[0,1,1]
	v_pk_fma_f32 v[26:27], v[98:99], v[102:103], v[26:27] op_sel:[1,0,0]
	v_pk_fma_f32 v[40:41], v[96:97], v[104:105], v[40:41] op_sel_hi:[0,1,1]
	v_pk_fma_f32 v[32:33], v[96:97], v[104:105], v[32:33] op_sel:[1,0,0]
	v_pk_fma_f32 v[22:23], v[98:99], v[104:105], v[22:23] op_sel_hi:[0,1,1]
	v_pk_fma_f32 v[18:19], v[98:99], v[104:105], v[18:19] op_sel:[1,0,0]
	v_pk_fma_f32 v[36:37], v[96:97], v[106:107], v[36:37] op_sel_hi:[0,1,1]
	v_pk_fma_f32 v[28:29], v[96:97], v[106:107], v[28:29] op_sel:[1,0,0]
	v_pk_fma_f32 v[20:21], v[98:99], v[106:107], v[20:21] op_sel_hi:[0,1,1]
	v_pk_fma_f32 v[16:17], v[98:99], v[106:107], v[16:17] op_sel:[1,0,0]
	ds_read_b128 v[96:99], v87 offset:2240
	s_waitcnt vmcnt(29) lgkmcnt(1)
	v_cvt_pk_f32_fp8_e32 v[100:101], v54
	v_cvt_pk_f32_fp8_sdwa v[102:103], v54 src0_sel:WORD_1
	v_cvt_pk_f32_fp8_e32 v[104:105], v55
	v_cvt_pk_f32_fp8_sdwa v[106:107], v55 src0_sel:WORD_1
	v_pk_fma_f32 v[48:49], v[92:93], v[100:101], v[48:49] op_sel_hi:[0,1,1]
	v_pk_fma_f32 v[44:45], v[92:93], v[100:101], v[44:45] op_sel:[1,0,0]
	v_pk_fma_f32 v[38:39], v[94:95], v[100:101], v[38:39] op_sel_hi:[0,1,1]
	v_pk_fma_f32 v[30:31], v[94:95], v[100:101], v[30:31] op_sel:[1,0,0]
	v_pk_fma_f32 v[46:47], v[92:93], v[102:103], v[46:47] op_sel_hi:[0,1,1]
	v_pk_fma_f32 v[42:43], v[92:93], v[102:103], v[42:43] op_sel:[1,0,0]
	v_pk_fma_f32 v[34:35], v[94:95], v[102:103], v[34:35] op_sel_hi:[0,1,1]
	v_pk_fma_f32 v[26:27], v[94:95], v[102:103], v[26:27] op_sel:[1,0,0]
	v_pk_fma_f32 v[40:41], v[92:93], v[104:105], v[40:41] op_sel_hi:[0,1,1]
	v_pk_fma_f32 v[32:33], v[92:93], v[104:105], v[32:33] op_sel:[1,0,0]
	v_pk_fma_f32 v[22:23], v[94:95], v[104:105], v[22:23] op_sel_hi:[0,1,1]
	v_pk_fma_f32 v[18:19], v[94:95], v[104:105], v[18:19] op_sel:[1,0,0]
	v_pk_fma_f32 v[36:37], v[92:93], v[106:107], v[36:37] op_sel_hi:[0,1,1]
	v_pk_fma_f32 v[28:29], v[92:93], v[106:107], v[28:29] op_sel:[1,0,0]
	v_pk_fma_f32 v[20:21], v[94:95], v[106:107], v[20:21] op_sel_hi:[0,1,1]
	v_pk_fma_f32 v[16:17], v[94:95], v[106:107], v[16:17] op_sel:[1,0,0]
	ds_read_b128 v[92:95], v87 offset:2304
	s_waitcnt vmcnt(28) lgkmcnt(1)
; DI void attn_item(const P& p, int b, int kvh, int quad4, char* smem, const AttnPre& pre) {
;     ...
;     for (int u = 0; u < 16; ++u) vv[u] = *(const uint2*)(vb + (size_t)idx[n0 + 4 * u + quad] * 256);
; #pragma unroll
;     for (int u = 0; u < 16; ++u) {
;       const float4 p4 = *(const float4*)(L + (n0 + 4 * u + quad) * 4);
;       const f32x2_t c0 = __builtin_amdgcn_cvt_pk_f32_fp8((int)vv[u].x, false), c1 = __builtin_amdgcn_cvt_pk_f32_fp8((int)vv[u].x, true);
;       const f32x2_t c2 = __builtin_amdgcn_cvt_pk_f32_fp8((int)vv[u].y, false), c3 = __builtin_amdgcn_cvt_pk_f32_fp8((int)vv[u].y, true);
;       const float vf[8] = {c0.x, c0.y, c1.x, c1.y, c2.x, c2.y, c3.x, c3.y};
; #pragma unroll
;       for (int e = 0; e < 8; ++e) {
;         o[0][e] = fmaf(p4.x, vf[e], o[0][e]); o[1][e] = fmaf(p4.y, vf[e], o[1][e]);
;         o[2][e] = fmaf(p4.z, vf[e], o[2][e]); o[3][e] = fmaf(p4.w, vf[e], o[3][e]);
;       }
	v_cvt_pk_f32_fp8_e32 v[100:101], v56
	v_cvt_pk_f32_fp8_sdwa v[102:103], v56 src0_sel:WORD_1
	v_cvt_pk_f32_fp8_e32 v[104:105], v57
	v_cvt_pk_f32_fp8_sdwa v[106:107], v57 src0_sel:WORD_1
	v_pk_fma_f32 v[48:49], v[96:97], v[100:101], v[48:49] op_sel_hi:[0,1,1]
	v_pk_fma_f32 v[44:45], v[96:97], v[100:101], v[44:45] op_sel:[1,0,0]
	v_pk_fma_f32 v[38:39], v[98:99], v[100:101], v[38:39] op_sel_hi:[0,1,1]
	v_pk_fma_f32 v[30:31], v[98:99], v[100:101], v[30:31] op_sel:[1,0,0]
	v_pk_fma_f32 v[46:47], v[96:97], v[102:103], v[46:47] op_sel_hi:[0,1,1]
	v_pk_fma_f32 v[42:43], v[96:97], v[102:103], v[42:43] op_sel:[1,0,0]
	v_pk_fma_f32 v[34:35], v[98:99], v[102:103], v[34:35] op_sel_hi:[0,1,1]
	v_pk_fma_f32 v[26:27], v[98:99], v[102:103], v[26:27] op_sel:[1,0,0]
	v_pk_fma_f32 v[40:41], v[96:97], v[104:105], v[40:41] op_sel_hi:[0,1,1]
	v_pk_fma_f32 v[32:33], v[96:97], v[104:105], v[32:33] op_sel:[1,0,0]
	v_pk_fma_f32 v[22:23], v[98:99], v[104:105], v[22:23] op_sel_hi:[0,1,1]
	v_pk_fma_f32 v[18:19], v[98:99], v[104:105], v[18:19] op_sel:[1,0,0]
	v_pk_fma_f32 v[36:37], v[96:97], v[106:107], v[36:37] op_sel_hi:[0,1,1]
	v_pk_fma_f32 v[28:29], v[96:97], v[106:107], v[28:29] op_sel:[1,0,0]
	v_pk_fma_f32 v[20:21], v[98:99], v[106:107], v[20:21] op_sel_hi:[0,1,1]
	v_pk_fma_f32 v[16:17], v[98:99], v[106:107], v[16:17] op_sel:[1,0,0]
	ds_read_b128 v[96:99], v87 offset:2368
	s_waitcnt vmcnt(27) lgkmcnt(1)
	v_cvt_pk_f32_fp8_e32 v[100:101], v58
	v_cvt_pk_f32_fp8_sdwa v[102:103], v58 src0_sel:WORD_1
	v_cvt_pk_f32_fp8_e32 v[104:105], v59
	v_cvt_pk_f32_fp8_sdwa v[106:107], v59 src0_sel:WORD_1
	v_pk_fma_f32 v[48:49], v[92:93], v[100:101], v[48:49] op_sel_hi:[0,1,1]
	v_pk_fma_f32 v[44:45], v[92:93], v[100:101], v[44:45] op_sel:[1,0,0]
	v_pk_fma_f32 v[38:39], v[94:95], v[100:101], v[38:39] op_sel_hi:[0,1,1]
	v_pk_fma_f32 v[30:31], v[94:95], v[100:101], v[30:31] op_sel:[1,0,0]
	v_pk_fma_f32 v[46:47], v[92:93], v[102:103], v[46:47] op_sel_hi:[0,1,1]
	v_pk_fma_f32 v[42:43], v[92:93], v[102:103], v[42:43] op_sel:[1,0,0]
	v_pk_fma_f32 v[34:35], v[94:95], v[102:103], v[34:35] op_sel_hi:[0,1,1]
	v_pk_fma_f32 v[26:27], v[94:95], v[102:103], v[26:27] op_sel:[1,0,0]
	v_pk_fma_f32 v[40:41], v[92:93], v[104:105], v[40:41] op_sel_hi:[0,1,1]
	v_pk_fma_f32 v[32:33], v[92:93], v[104:105], v[32:33] op_sel:[1,0,0]
	v_pk_fma_f32 v[22:23], v[94:95], v[104:105], v[22:23] op_sel_hi:[0,1,1]
	v_pk_fma_f32 v[18:19], v[94:95], v[104:105], v[18:19] op_sel:[1,0,0]
	v_pk_fma_f32 v[36:37], v[92:93], v[106:107], v[36:37] op_sel_hi:[0,1,1]
	v_pk_fma_f32 v[28:29], v[92:93], v[106:107], v[28:29] op_sel:[1,0,0]
	v_pk_fma_f32 v[20:21], v[94:95], v[106:107], v[20:21] op_sel_hi:[0,1,1]
	v_pk_fma_f32 v[16:17], v[94:95], v[106:107], v[16:17] op_sel:[1,0,0]
	ds_read_b128 v[92:95], v87 offset:2432
	s_waitcnt vmcnt(26) lgkmcnt(1)
	v_cvt_pk_f32_fp8_e32 v[100:101], v60
	v_cvt_pk_f32_fp8_sdwa v[102:103], v60 src0_sel:WORD_1
	v_cvt_pk_f32_fp8_e32 v[104:105], v61
	v_cvt_pk_f32_fp8_sdwa v[106:107], v61 src0_sel:WORD_1
	v_pk_fma_f32 v[48:49], v[96:97], v[100:101], v[48:49] op_sel_hi:[0,1,1]
	v_pk_fma_f32 v[44:45], v[96:97], v[100:101], v[44:45] op_sel:[1,0,0]
	v_pk_fma_f32 v[38:39], v[98:99], v[100:101], v[38:39] op_sel_hi:[0,1,1]
	v_pk_fma_f32 v[30:31], v[98:99], v[100:101], v[30:31] op_sel:[1,0,0]
	v_pk_fma_f32 v[46:47], v[96:97], v[102:103], v[46:47] op_sel_hi:[0,1,1]
	v_pk_fma_f32 v[42:43], v[96:97], v[102:103], v[42:43] op_sel:[1,0,0]
	v_pk_fma_f32 v[34:35], v[98:99], v[102:103], v[34:35] op_sel_hi:[0,1,1]
	v_pk_fma_f32 v[26:27], v[98:99], v[102:103], v[26:27] op_sel:[1,0,0]
	v_pk_fma_f32 v[40:41], v[96:97], v[104:105], v[40:41] op_sel_hi:[0,1,1]
	v_pk_fma_f32 v[32:33], v[96:97], v[104:105], v[32:33] op_sel:[1,0,0]
	v_pk_fma_f32 v[22:23], v[98:99], v[104:105], v[22:23] op_sel_hi:[0,1,1]
	v_pk_fma_f32 v[18:19], v[98:99], v[104:105], v[18:19] op_sel:[1,0,0]
	v_pk_fma_f32 v[36:37], v[96:97], v[106:107], v[36:37] op_sel_hi:[0,1,1]
	v_pk_fma_f32 v[28:29], v[96:97], v[106:107], v[28:29] op_sel:[1,0,0]
	v_pk_fma_f32 v[20:21], v[98:99], v[106:107], v[20:21] op_sel_hi:[0,1,1]
	v_pk_fma_f32 v[16:17], v[98:99], v[106:107], v[16:17] op_sel:[1,0,0]
	ds_read_b128 v[96:99], v87 offset:2496
	s_waitcnt vmcnt(25) lgkmcnt(1)
	v_cvt_pk_f32_fp8_e32 v[100:101], v62
	v_cvt_pk_f32_fp8_sdwa v[102:103], v62 src0_sel:WORD_1
	v_cvt_pk_f32_fp8_e32 v[104:105], v63
	v_cvt_pk_f32_fp8_sdwa v[106:107], v63 src0_sel:WORD_1
	v_pk_fma_f32 v[48:49], v[92:93], v[100:101], v[48:49] op_sel_hi:[0,1,1]
	v_pk_fma_f32 v[44:45], v[92:93], v[100:101], v[44:45] op_sel:[1,0,0]
	v_pk_fma_f32 v[38:39], v[94:95], v[100:101], v[38:39] op_sel_hi:[0,1,1]
	v_pk_fma_f32 v[30:31], v[94:95], v[100:101], v[30:31] op_sel:[1,0,0]
	v_pk_fma_f32 v[46:47], v[92:93], v[102:103], v[46:47] op_sel_hi:[0,1,1]
	v_pk_fma_f32 v[42:43], v[92:93], v[102:103], v[42:43] op_sel:[1,0,0]
	v_pk_fma_f32 v[34:35], v[94:95], v[102:103], v[34:35] op_sel_hi:[0,1,1]
	v_pk_fma_f32 v[26:27], v[94:95], v[102:103], v[26:27] op_sel:[1,0,0]
	v_pk_fma_f32 v[40:41], v[92:93], v[104:105], v[40:41] op_sel_hi:[0,1,1]
	v_pk_fma_f32 v[32:33], v[92:93], v[104:105], v[32:33] op_sel:[1,0,0]
	v_pk_fma_f32 v[22:23], v[94:95], v[104:105], v[22:23] op_sel_hi:[0,1,1]
	v_pk_fma_f32 v[18:19], v[94:95], v[104:105], v[18:19] op_sel:[1,0,0]
	v_pk_fma_f32 v[36:37], v[92:93], v[106:107], v[36:37] op_sel_hi:[0,1,1]
	v_pk_fma_f32 v[28:29], v[92:93], v[106:107], v[28:29] op_sel:[1,0,0]
	v_pk_fma_f32 v[20:21], v[94:95], v[106:107], v[20:21] op_sel_hi:[0,1,1]
	v_pk_fma_f32 v[16:17], v[94:95], v[106:107], v[16:17] op_sel:[1,0,0]
	ds_read_b128 v[92:95], v87 offset:2560
	s_waitcnt vmcnt(24) lgkmcnt(1)
; DI void attn_item(const P& p, int b, int kvh, int quad4, char* smem, const AttnPre& pre) {
;     ...
;     for (int u = 0; u < 16; ++u) vv[u] = *(const uint2*)(vb + (size_t)idx[n0 + 4 * u + quad] * 256);
; #pragma unroll
;     for (int u = 0; u < 16; ++u) {
;       const float4 p4 = *(const float4*)(L + (n0 + 4 * u + quad) * 4);
;       const f32x2_t c0 = __builtin_amdgcn_cvt_pk_f32_fp8((int)vv[u].x, false), c1 = __builtin_amdgcn_cvt_pk_f32_fp8((int)vv[u].x, true);
;       const f32x2_t c2 = __builtin_amdgcn_cvt_pk_f32_fp8((int)vv[u].y, false), c3 = __builtin_amdgcn_cvt_pk_f32_fp8((int)vv[u].y, true);
;       const float vf[8] = {c0.x, c0.y, c1.x, c1.y, c2.x, c2.y, c3.x, c3.y};
; #pragma unroll
;       for (int e = 0; e < 8; ++e) {
;         o[0][e] = fmaf(p4.x, vf[e], o[0][e]); o[1][e] = fmaf(p4.y, vf[e], o[1][e]);
;         o[2][e] = fmaf(p4.z, vf[e], o[2][e]); o[3][e] = fmaf(p4.w, vf[e], o[3][e]);
;       }
	v_cvt_pk_f32_fp8_e32 v[100:101], v64
	v_cvt_pk_f32_fp8_sdwa v[102:103], v64 src0_sel:WORD_1
	v_cvt_pk_f32_fp8_e32 v[104:105], v65
	v_cvt_pk_f32_fp8_sdwa v[106:107], v65 src0_sel:WORD_1
	v_pk_fma_f32 v[48:49], v[96:97], v[100:101], v[48:49] op_sel_hi:[0,1,1]
	v_pk_fma_f32 v[44:45], v[96:97], v[100:101], v[44:45] op_sel:[1,0,0]
	v_pk_fma_f32 v[38:39], v[98:99], v[100:101], v[38:39] op_sel_hi:[0,1,1]
	v_pk_fma_f32 v[30:31], v[98:99], v[100:101], v[30:31] op_sel:[1,0,0]
	v_pk_fma_f32 v[46:47], v[96:97], v[102:103], v[46:47] op_sel_hi:[0,1,1]
	v_pk_fma_f32 v[42:43], v[96:97], v[102:103], v[42:43] op_sel:[1,0,0]
	v_pk_fma_f32 v[34:35], v[98:99], v[102:103], v[34:35] op_sel_hi:[0,1,1]
	v_pk_fma_f32 v[26:27], v[98:99], v[102:103], v[26:27] op_sel:[1,0,0]
	v_pk_fma_f32 v[40:41], v[96:97], v[104:105], v[40:41] op_sel_hi:[0,1,1]
	v_pk_fma_f32 v[32:33], v[96:97], v[104:105], v[32:33] op_sel:[1,0,0]
	v_pk_fma_f32 v[22:23], v[98:99], v[104:105], v[22:23] op_sel_hi:[0,1,1]
	v_pk_fma_f32 v[18:19], v[98:99], v[104:105], v[18:19] op_sel:[1,0,0]
	v_pk_fma_f32 v[36:37], v[96:97], v[106:107], v[36:37] op_sel_hi:[0,1,1]
	v_pk_fma_f32 v[28:29], v[96:97], v[106:107], v[28:29] op_sel:[1,0,0]
	v_pk_fma_f32 v[20:21], v[98:99], v[106:107], v[20:21] op_sel_hi:[0,1,1]
	v_pk_fma_f32 v[16:17], v[98:99], v[106:107], v[16:17] op_sel:[1,0,0]
	ds_read_b128 v[96:99], v87 offset:2624
	s_waitcnt vmcnt(23) lgkmcnt(1)
	v_cvt_pk_f32_fp8_e32 v[100:101], v66
	v_cvt_pk_f32_fp8_sdwa v[102:103], v66 src0_sel:WORD_1
	v_cvt_pk_f32_fp8_e32 v[104:105], v67
	v_cvt_pk_f32_fp8_sdwa v[106:107], v67 src0_sel:WORD_1
	v_pk_fma_f32 v[48:49], v[92:93], v[100:101], v[48:49] op_sel_hi:[0,1,1]
	v_pk_fma_f32 v[44:45], v[92:93], v[100:101], v[44:45] op_sel:[1,0,0]
	v_pk_fma_f32 v[38:39], v[94:95], v[100:101], v[38:39] op_sel_hi:[0,1,1]
	v_pk_fma_f32 v[30:31], v[94:95], v[100:101], v[30:31] op_sel:[1,0,0]
	v_pk_fma_f32 v[46:47], v[92:93], v[102:103], v[46:47] op_sel_hi:[0,1,1]
	v_pk_fma_f32 v[42:43], v[92:93], v[102:103], v[42:43] op_sel:[1,0,0]
	v_pk_fma_f32 v[34:35], v[94:95], v[102:103], v[34:35] op_sel_hi:[0,1,1]
	v_pk_fma_f32 v[26:27], v[94:95], v[102:103], v[26:27] op_sel:[1,0,0]
	v_pk_fma_f32 v[40:41], v[92:93], v[104:105], v[40:41] op_sel_hi:[0,1,1]
	v_pk_fma_f32 v[32:33], v[92:93], v[104:105], v[32:33] op_sel:[1,0,0]
	v_pk_fma_f32 v[22:23], v[94:95], v[104:105], v[22:23] op_sel_hi:[0,1,1]
	v_pk_fma_f32 v[18:19], v[94:95], v[104:105], v[18:19] op_sel:[1,0,0]
	v_pk_fma_f32 v[36:37], v[92:93], v[106:107], v[36:37] op_sel_hi:[0,1,1]
	v_pk_fma_f32 v[28:29], v[92:93], v[106:107], v[28:29] op_sel:[1,0,0]
	v_pk_fma_f32 v[20:21], v[94:95], v[106:107], v[20:21] op_sel_hi:[0,1,1]
	v_pk_fma_f32 v[16:17], v[94:95], v[106:107], v[16:17] op_sel:[1,0,0]
	ds_read_b128 v[92:95], v87 offset:2688
	s_waitcnt vmcnt(22) lgkmcnt(1)
	v_cvt_pk_f32_fp8_e32 v[100:101], v68
	v_cvt_pk_f32_fp8_sdwa v[102:103], v68 src0_sel:WORD_1
	v_cvt_pk_f32_fp8_e32 v[104:105], v69
	v_cvt_pk_f32_fp8_sdwa v[106:107], v69 src0_sel:WORD_1
	v_pk_fma_f32 v[48:49], v[96:97], v[100:101], v[48:49] op_sel_hi:[0,1,1]
	v_pk_fma_f32 v[44:45], v[96:97], v[100:101], v[44:45] op_sel:[1,0,0]
	v_pk_fma_f32 v[38:39], v[98:99], v[100:101], v[38:39] op_sel_hi:[0,1,1]
	v_pk_fma_f32 v[30:31], v[98:99], v[100:101], v[30:31] op_sel:[1,0,0]
	v_pk_fma_f32 v[46:47], v[96:97], v[102:103], v[46:47] op_sel_hi:[0,1,1]
	v_pk_fma_f32 v[42:43], v[96:97], v[102:103], v[42:43] op_sel:[1,0,0]
	v_pk_fma_f32 v[34:35], v[98:99], v[102:103], v[34:35] op_sel_hi:[0,1,1]
	v_pk_fma_f32 v[26:27], v[98:99], v[102:103], v[26:27] op_sel:[1,0,0]
	v_pk_fma_f32 v[40:41], v[96:97], v[104:105], v[40:41] op_sel_hi:[0,1,1]
	v_pk_fma_f32 v[32:33], v[96:97], v[104:105], v[32:33] op_sel:[1,0,0]
	v_pk_fma_f32 v[22:23], v[98:99], v[104:105], v[22:23] op_sel_hi:[0,1,1]
	v_pk_fma_f32 v[18:19], v[98:99], v[104:105], v[18:19] op_sel:[1,0,0]
	v_pk_fma_f32 v[36:37], v[96:97], v[106:107], v[36:37] op_sel_hi:[0,1,1]
	v_pk_fma_f32 v[28:29], v[96:97], v[106:107], v[28:29] op_sel:[1,0,0]
	v_pk_fma_f32 v[20:21], v[98:99], v[106:107], v[20:21] op_sel_hi:[0,1,1]
	v_pk_fma_f32 v[16:17], v[98:99], v[106:107], v[16:17] op_sel:[1,0,0]
	ds_read_b128 v[96:99], v87 offset:2752
	s_waitcnt vmcnt(21) lgkmcnt(1)
	v_cvt_pk_f32_fp8_e32 v[100:101], v70
	v_cvt_pk_f32_fp8_sdwa v[102:103], v70 src0_sel:WORD_1
	v_cvt_pk_f32_fp8_e32 v[104:105], v71
	v_cvt_pk_f32_fp8_sdwa v[106:107], v71 src0_sel:WORD_1
	v_pk_fma_f32 v[48:49], v[92:93], v[100:101], v[48:49] op_sel_hi:[0,1,1]
	v_pk_fma_f32 v[44:45], v[92:93], v[100:101], v[44:45] op_sel:[1,0,0]
	v_pk_fma_f32 v[38:39], v[94:95], v[100:101], v[38:39] op_sel_hi:[0,1,1]
	v_pk_fma_f32 v[30:31], v[94:95], v[100:101], v[30:31] op_sel:[1,0,0]
	v_pk_fma_f32 v[46:47], v[92:93], v[102:103], v[46:47] op_sel_hi:[0,1,1]
	v_pk_fma_f32 v[42:43], v[92:93], v[102:103], v[42:43] op_sel:[1,0,0]
	v_pk_fma_f32 v[34:35], v[94:95], v[102:103], v[34:35] op_sel_hi:[0,1,1]
	v_pk_fma_f32 v[26:27], v[94:95], v[102:103], v[26:27] op_sel:[1,0,0]
	v_pk_fma_f32 v[40:41], v[92:93], v[104:105], v[40:41] op_sel_hi:[0,1,1]
	v_pk_fma_f32 v[32:33], v[92:93], v[104:105], v[32:33] op_sel:[1,0,0]
	v_pk_fma_f32 v[22:23], v[94:95], v[104:105], v[22:23] op_sel_hi:[0,1,1]
	v_pk_fma_f32 v[18:19], v[94:95], v[104:105], v[18:19] op_sel:[1,0,0]
	v_pk_fma_f32 v[36:37], v[92:93], v[106:107], v[36:37] op_sel_hi:[0,1,1]
	v_pk_fma_f32 v[28:29], v[92:93], v[106:107], v[28:29] op_sel:[1,0,0]
	v_pk_fma_f32 v[20:21], v[94:95], v[106:107], v[20:21] op_sel_hi:[0,1,1]
	v_pk_fma_f32 v[16:17], v[94:95], v[106:107], v[16:17] op_sel:[1,0,0]
	ds_read_b128 v[92:95], v87 offset:2816
	s_waitcnt vmcnt(20) lgkmcnt(1)
; DI void attn_item(const P& p, int b, int kvh, int quad4, char* smem, const AttnPre& pre) {
;     ...
;     for (int u = 0; u < 16; ++u) vv[u] = *(const uint2*)(vb + (size_t)idx[n0 + 4 * u + quad] * 256);
; #pragma unroll
;     for (int u = 0; u < 16; ++u) {
;       const float4 p4 = *(const float4*)(L + (n0 + 4 * u + quad) * 4);
;       const f32x2_t c0 = __builtin_amdgcn_cvt_pk_f32_fp8((int)vv[u].x, false), c1 = __builtin_amdgcn_cvt_pk_f32_fp8((int)vv[u].x, true);
;       const f32x2_t c2 = __builtin_amdgcn_cvt_pk_f32_fp8((int)vv[u].y, false), c3 = __builtin_amdgcn_cvt_pk_f32_fp8((int)vv[u].y, true);
;       const float vf[8] = {c0.x, c0.y, c1.x, c1.y, c2.x, c2.y, c3.x, c3.y};
; #pragma unroll
;       for (int e = 0; e < 8; ++e) {
;         o[0][e] = fmaf(p4.x, vf[e], o[0][e]); o[1][e] = fmaf(p4.y, vf[e], o[1][e]);
;         o[2][e] = fmaf(p4.z, vf[e], o[2][e]); o[3][e] = fmaf(p4.w, vf[e], o[3][e]);
;       }
	v_cvt_pk_f32_fp8_e32 v[100:101], v72
	v_cvt_pk_f32_fp8_sdwa v[102:103], v72 src0_sel:WORD_1
	v_cvt_pk_f32_fp8_e32 v[104:105], v73
	v_cvt_pk_f32_fp8_sdwa v[106:107], v73 src0_sel:WORD_1
	v_pk_fma_f32 v[48:49], v[96:97], v[100:101], v[48:49] op_sel_hi:[0,1,1]
	v_pk_fma_f32 v[44:45], v[96:97], v[100:101], v[44:45] op_sel:[1,0,0]
	v_pk_fma_f32 v[38:39], v[98:99], v[100:101], v[38:39] op_sel_hi:[0,1,1]
	v_pk_fma_f32 v[30:31], v[98:99], v[100:101], v[30:31] op_sel:[1,0,0]
	v_pk_fma_f32 v[46:47], v[96:97], v[102:103], v[46:47] op_sel_hi:[0,1,1]
	v_pk_fma_f32 v[42:43], v[96:97], v[102:103], v[42:43] op_sel:[1,0,0]
	v_pk_fma_f32 v[34:35], v[98:99], v[102:103], v[34:35] op_sel_hi:[0,1,1]
	v_pk_fma_f32 v[26:27], v[98:99], v[102:103], v[26:27] op_sel:[1,0,0]
	v_pk_fma_f32 v[40:41], v[96:97], v[104:105], v[40:41] op_sel_hi:[0,1,1]
	v_pk_fma_f32 v[32:33], v[96:97], v[104:105], v[32:33] op_sel:[1,0,0]
	v_pk_fma_f32 v[22:23], v[98:99], v[104:105], v[22:23] op_sel_hi:[0,1,1]
	v_pk_fma_f32 v[18:19], v[98:99], v[104:105], v[18:19] op_sel:[1,0,0]
	v_pk_fma_f32 v[36:37], v[96:97], v[106:107], v[36:37] op_sel_hi:[0,1,1]
	v_pk_fma_f32 v[28:29], v[96:97], v[106:107], v[28:29] op_sel:[1,0,0]
	v_pk_fma_f32 v[20:21], v[98:99], v[106:107], v[20:21] op_sel_hi:[0,1,1]
	v_pk_fma_f32 v[16:17], v[98:99], v[106:107], v[16:17] op_sel:[1,0,0]
	ds_read_b128 v[96:99], v87 offset:2880
	s_waitcnt vmcnt(19) lgkmcnt(1)
	v_cvt_pk_f32_fp8_e32 v[100:101], v74
	v_cvt_pk_f32_fp8_sdwa v[102:103], v74 src0_sel:WORD_1
	v_cvt_pk_f32_fp8_e32 v[104:105], v75
	v_cvt_pk_f32_fp8_sdwa v[106:107], v75 src0_sel:WORD_1
	v_pk_fma_f32 v[48:49], v[92:93], v[100:101], v[48:49] op_sel_hi:[0,1,1]
	v_pk_fma_f32 v[44:45], v[92:93], v[100:101], v[44:45] op_sel:[1,0,0]
	v_pk_fma_f32 v[38:39], v[94:95], v[100:101], v[38:39] op_sel_hi:[0,1,1]
	v_pk_fma_f32 v[30:31], v[94:95], v[100:101], v[30:31] op_sel:[1,0,0]
	v_pk_fma_f32 v[46:47], v[92:93], v[102:103], v[46:47] op_sel_hi:[0,1,1]
	v_pk_fma_f32 v[42:43], v[92:93], v[102:103], v[42:43] op_sel:[1,0,0]
	v_pk_fma_f32 v[34:35], v[94:95], v[102:103], v[34:35] op_sel_hi:[0,1,1]
	v_pk_fma_f32 v[26:27], v[94:95], v[102:103], v[26:27] op_sel:[1,0,0]
	v_pk_fma_f32 v[40:41], v[92:93], v[104:105], v[40:41] op_sel_hi:[0,1,1]
	v_pk_fma_f32 v[32:33], v[92:93], v[104:105], v[32:33] op_sel:[1,0,0]
	v_pk_fma_f32 v[22:23], v[94:95], v[104:105], v[22:23] op_sel_hi:[0,1,1]
	v_pk_fma_f32 v[18:19], v[94:95], v[104:105], v[18:19] op_sel:[1,0,0]
	v_pk_fma_f32 v[36:37], v[92:93], v[106:107], v[36:37] op_sel_hi:[0,1,1]
	v_pk_fma_f32 v[28:29], v[92:93], v[106:107], v[28:29] op_sel:[1,0,0]
	v_pk_fma_f32 v[20:21], v[94:95], v[106:107], v[20:21] op_sel_hi:[0,1,1]
	v_pk_fma_f32 v[16:17], v[94:95], v[106:107], v[16:17] op_sel:[1,0,0]
	ds_read_b128 v[92:95], v87 offset:2944
	s_waitcnt vmcnt(18) lgkmcnt(1)
	v_cvt_pk_f32_fp8_e32 v[100:101], v76
	v_cvt_pk_f32_fp8_sdwa v[102:103], v76 src0_sel:WORD_1
	v_cvt_pk_f32_fp8_e32 v[104:105], v77
	v_cvt_pk_f32_fp8_sdwa v[106:107], v77 src0_sel:WORD_1
	v_pk_fma_f32 v[48:49], v[96:97], v[100:101], v[48:49] op_sel_hi:[0,1,1]
	v_pk_fma_f32 v[44:45], v[96:97], v[100:101], v[44:45] op_sel:[1,0,0]
	v_pk_fma_f32 v[38:39], v[98:99], v[100:101], v[38:39] op_sel_hi:[0,1,1]
	v_pk_fma_f32 v[30:31], v[98:99], v[100:101], v[30:31] op_sel:[1,0,0]
	v_pk_fma_f32 v[46:47], v[96:97], v[102:103], v[46:47] op_sel_hi:[0,1,1]
	v_pk_fma_f32 v[42:43], v[96:97], v[102:103], v[42:43] op_sel:[1,0,0]
	v_pk_fma_f32 v[34:35], v[98:99], v[102:103], v[34:35] op_sel_hi:[0,1,1]
	v_pk_fma_f32 v[26:27], v[98:99], v[102:103], v[26:27] op_sel:[1,0,0]
	v_pk_fma_f32 v[40:41], v[96:97], v[104:105], v[40:41] op_sel_hi:[0,1,1]
	v_pk_fma_f32 v[32:33], v[96:97], v[104:105], v[32:33] op_sel:[1,0,0]
	v_pk_fma_f32 v[22:23], v[98:99], v[104:105], v[22:23] op_sel_hi:[0,1,1]
	v_pk_fma_f32 v[18:19], v[98:99], v[104:105], v[18:19] op_sel:[1,0,0]
	v_pk_fma_f32 v[36:37], v[96:97], v[106:107], v[36:37] op_sel_hi:[0,1,1]
	v_pk_fma_f32 v[28:29], v[96:97], v[106:107], v[28:29] op_sel:[1,0,0]
	v_pk_fma_f32 v[20:21], v[98:99], v[106:107], v[20:21] op_sel_hi:[0,1,1]
	v_pk_fma_f32 v[16:17], v[98:99], v[106:107], v[16:17] op_sel:[1,0,0]
	ds_read_b128 v[96:99], v87 offset:3008
	s_waitcnt vmcnt(17) lgkmcnt(1)
	v_cvt_pk_f32_fp8_e32 v[100:101], v78
	v_cvt_pk_f32_fp8_sdwa v[102:103], v78 src0_sel:WORD_1
	v_cvt_pk_f32_fp8_e32 v[104:105], v79
	v_cvt_pk_f32_fp8_sdwa v[106:107], v79 src0_sel:WORD_1
	v_pk_fma_f32 v[48:49], v[92:93], v[100:101], v[48:49] op_sel_hi:[0,1,1]
	v_pk_fma_f32 v[44:45], v[92:93], v[100:101], v[44:45] op_sel:[1,0,0]
	v_pk_fma_f32 v[38:39], v[94:95], v[100:101], v[38:39] op_sel_hi:[0,1,1]
	v_pk_fma_f32 v[30:31], v[94:95], v[100:101], v[30:31] op_sel:[1,0,0]
	v_pk_fma_f32 v[46:47], v[92:93], v[102:103], v[46:47] op_sel_hi:[0,1,1]
	v_pk_fma_f32 v[42:43], v[92:93], v[102:103], v[42:43] op_sel:[1,0,0]
	v_pk_fma_f32 v[34:35], v[94:95], v[102:103], v[34:35] op_sel_hi:[0,1,1]
	v_pk_fma_f32 v[26:27], v[94:95], v[102:103], v[26:27] op_sel:[1,0,0]
	v_pk_fma_f32 v[40:41], v[92:93], v[104:105], v[40:41] op_sel_hi:[0,1,1]
	v_pk_fma_f32 v[32:33], v[92:93], v[104:105], v[32:33] op_sel:[1,0,0]
	v_pk_fma_f32 v[22:23], v[94:95], v[104:105], v[22:23] op_sel_hi:[0,1,1]
	v_pk_fma_f32 v[18:19], v[94:95], v[104:105], v[18:19] op_sel:[1,0,0]
	v_pk_fma_f32 v[36:37], v[92:93], v[106:107], v[36:37] op_sel_hi:[0,1,1]
	v_pk_fma_f32 v[28:29], v[92:93], v[106:107], v[28:29] op_sel:[1,0,0]
	v_pk_fma_f32 v[20:21], v[94:95], v[106:107], v[20:21] op_sel_hi:[0,1,1]
	v_pk_fma_f32 v[16:17], v[94:95], v[106:107], v[16:17] op_sel:[1,0,0]
	ds_read_b128 v[92:95], v87 offset:3072
	s_waitcnt vmcnt(16) lgkmcnt(1)
; DI void attn_item(const P& p, int b, int kvh, int quad4, char* smem, const AttnPre& pre) {
;     ...
;     for (int u = 0; u < 16; ++u) vv[u] = *(const uint2*)(vb + (size_t)idx[n0 + 4 * u + quad] * 256);
; #pragma unroll
;     for (int u = 0; u < 16; ++u) {
;       const float4 p4 = *(const float4*)(L + (n0 + 4 * u + quad) * 4);
;       const f32x2_t c0 = __builtin_amdgcn_cvt_pk_f32_fp8((int)vv[u].x, false), c1 = __builtin_amdgcn_cvt_pk_f32_fp8((int)vv[u].x, true);
;       const f32x2_t c2 = __builtin_amdgcn_cvt_pk_f32_fp8((int)vv[u].y, false), c3 = __builtin_amdgcn_cvt_pk_f32_fp8((int)vv[u].y, true);
;       const float vf[8] = {c0.x, c0.y, c1.x, c1.y, c2.x, c2.y, c3.x, c3.y};
; #pragma unroll
;       for (int e = 0; e < 8; ++e) {
;         o[0][e] = fmaf(p4.x, vf[e], o[0][e]); o[1][e] = fmaf(p4.y, vf[e], o[1][e]);
;         o[2][e] = fmaf(p4.z, vf[e], o[2][e]); o[3][e] = fmaf(p4.w, vf[e], o[3][e]);
;       }
	v_cvt_pk_f32_fp8_e32 v[100:101], v80
	v_cvt_pk_f32_fp8_sdwa v[102:103], v80 src0_sel:WORD_1
	v_cvt_pk_f32_fp8_e32 v[104:105], v81
	v_cvt_pk_f32_fp8_sdwa v[106:107], v81 src0_sel:WORD_1
	v_pk_fma_f32 v[48:49], v[96:97], v[100:101], v[48:49] op_sel_hi:[0,1,1]
	v_pk_fma_f32 v[44:45], v[96:97], v[100:101], v[44:45] op_sel:[1,0,0]
	v_pk_fma_f32 v[38:39], v[98:99], v[100:101], v[38:39] op_sel_hi:[0,1,1]
	v_pk_fma_f32 v[30:31], v[98:99], v[100:101], v[30:31] op_sel:[1,0,0]
	v_pk_fma_f32 v[46:47], v[96:97], v[102:103], v[46:47] op_sel_hi:[0,1,1]
	v_pk_fma_f32 v[42:43], v[96:97], v[102:103], v[42:43] op_sel:[1,0,0]
	v_pk_fma_f32 v[34:35], v[98:99], v[102:103], v[34:35] op_sel_hi:[0,1,1]
	v_pk_fma_f32 v[26:27], v[98:99], v[102:103], v[26:27] op_sel:[1,0,0]
	v_pk_fma_f32 v[40:41], v[96:97], v[104:105], v[40:41] op_sel_hi:[0,1,1]
	v_pk_fma_f32 v[32:33], v[96:97], v[104:105], v[32:33] op_sel:[1,0,0]
	v_pk_fma_f32 v[22:23], v[98:99], v[104:105], v[22:23] op_sel_hi:[0,1,1]
	v_pk_fma_f32 v[18:19], v[98:99], v[104:105], v[18:19] op_sel:[1,0,0]
	v_pk_fma_f32 v[36:37], v[96:97], v[106:107], v[36:37] op_sel_hi:[0,1,1]
	v_pk_fma_f32 v[28:29], v[96:97], v[106:107], v[28:29] op_sel:[1,0,0]
	v_pk_fma_f32 v[20:21], v[98:99], v[106:107], v[20:21] op_sel_hi:[0,1,1]
	v_pk_fma_f32 v[16:17], v[98:99], v[106:107], v[16:17] op_sel:[1,0,0]
	ds_read_b128 v[96:99], v87 offset:3136
	s_waitcnt vmcnt(15) lgkmcnt(1)
	v_cvt_pk_f32_fp8_e32 v[100:101], v120
	v_cvt_pk_f32_fp8_sdwa v[102:103], v120 src0_sel:WORD_1
	v_cvt_pk_f32_fp8_e32 v[104:105], v121
	v_cvt_pk_f32_fp8_sdwa v[106:107], v121 src0_sel:WORD_1
	v_pk_fma_f32 v[48:49], v[92:93], v[100:101], v[48:49] op_sel_hi:[0,1,1]
	v_pk_fma_f32 v[44:45], v[92:93], v[100:101], v[44:45] op_sel:[1,0,0]
	v_pk_fma_f32 v[38:39], v[94:95], v[100:101], v[38:39] op_sel_hi:[0,1,1]
	v_pk_fma_f32 v[30:31], v[94:95], v[100:101], v[30:31] op_sel:[1,0,0]
	v_pk_fma_f32 v[46:47], v[92:93], v[102:103], v[46:47] op_sel_hi:[0,1,1]
	v_pk_fma_f32 v[42:43], v[92:93], v[102:103], v[42:43] op_sel:[1,0,0]
	v_pk_fma_f32 v[34:35], v[94:95], v[102:103], v[34:35] op_sel_hi:[0,1,1]
	v_pk_fma_f32 v[26:27], v[94:95], v[102:103], v[26:27] op_sel:[1,0,0]
	v_pk_fma_f32 v[40:41], v[92:93], v[104:105], v[40:41] op_sel_hi:[0,1,1]
	v_pk_fma_f32 v[32:33], v[92:93], v[104:105], v[32:33] op_sel:[1,0,0]
	v_pk_fma_f32 v[22:23], v[94:95], v[104:105], v[22:23] op_sel_hi:[0,1,1]
	v_pk_fma_f32 v[18:19], v[94:95], v[104:105], v[18:19] op_sel:[1,0,0]
	v_pk_fma_f32 v[36:37], v[92:93], v[106:107], v[36:37] op_sel_hi:[0,1,1]
	v_pk_fma_f32 v[28:29], v[92:93], v[106:107], v[28:29] op_sel:[1,0,0]
	v_pk_fma_f32 v[20:21], v[94:95], v[106:107], v[20:21] op_sel_hi:[0,1,1]
	v_pk_fma_f32 v[16:17], v[94:95], v[106:107], v[16:17] op_sel:[1,0,0]
	ds_read_b128 v[92:95], v87 offset:3200
	s_waitcnt vmcnt(14) lgkmcnt(1)
	v_cvt_pk_f32_fp8_e32 v[100:101], v122
	v_cvt_pk_f32_fp8_sdwa v[102:103], v122 src0_sel:WORD_1
	v_cvt_pk_f32_fp8_e32 v[104:105], v123
	v_cvt_pk_f32_fp8_sdwa v[106:107], v123 src0_sel:WORD_1
	v_pk_fma_f32 v[48:49], v[96:97], v[100:101], v[48:49] op_sel_hi:[0,1,1]
	v_pk_fma_f32 v[44:45], v[96:97], v[100:101], v[44:45] op_sel:[1,0,0]
	v_pk_fma_f32 v[38:39], v[98:99], v[100:101], v[38:39] op_sel_hi:[0,1,1]
	v_pk_fma_f32 v[30:31], v[98:99], v[100:101], v[30:31] op_sel:[1,0,0]
	v_pk_fma_f32 v[46:47], v[96:97], v[102:103], v[46:47] op_sel_hi:[0,1,1]
	v_pk_fma_f32 v[42:43], v[96:97], v[102:103], v[42:43] op_sel:[1,0,0]
	v_pk_fma_f32 v[34:35], v[98:99], v[102:103], v[34:35] op_sel_hi:[0,1,1]
	v_pk_fma_f32 v[26:27], v[98:99], v[102:103], v[26:27] op_sel:[1,0,0]
	v_pk_fma_f32 v[40:41], v[96:97], v[104:105], v[40:41] op_sel_hi:[0,1,1]
	v_pk_fma_f32 v[32:33], v[96:97], v[104:105], v[32:33] op_sel:[1,0,0]
	v_pk_fma_f32 v[22:23], v[98:99], v[104:105], v[22:23] op_sel_hi:[0,1,1]
	v_pk_fma_f32 v[18:19], v[98:99], v[104:105], v[18:19] op_sel:[1,0,0]
	v_pk_fma_f32 v[36:37], v[96:97], v[106:107], v[36:37] op_sel_hi:[0,1,1]
	v_pk_fma_f32 v[28:29], v[96:97], v[106:107], v[28:29] op_sel:[1,0,0]
	v_pk_fma_f32 v[20:21], v[98:99], v[106:107], v[20:21] op_sel_hi:[0,1,1]
	v_pk_fma_f32 v[16:17], v[98:99], v[106:107], v[16:17] op_sel:[1,0,0]
	ds_read_b128 v[96:99], v87 offset:3264
	s_waitcnt vmcnt(13) lgkmcnt(1)
	v_cvt_pk_f32_fp8_e32 v[100:101], v124
	v_cvt_pk_f32_fp8_sdwa v[102:103], v124 src0_sel:WORD_1
	v_cvt_pk_f32_fp8_e32 v[104:105], v125
	v_cvt_pk_f32_fp8_sdwa v[106:107], v125 src0_sel:WORD_1
	v_pk_fma_f32 v[48:49], v[92:93], v[100:101], v[48:49] op_sel_hi:[0,1,1]
	v_pk_fma_f32 v[44:45], v[92:93], v[100:101], v[44:45] op_sel:[1,0,0]
	v_pk_fma_f32 v[38:39], v[94:95], v[100:101], v[38:39] op_sel_hi:[0,1,1]
	v_pk_fma_f32 v[30:31], v[94:95], v[100:101], v[30:31] op_sel:[1,0,0]
	v_pk_fma_f32 v[46:47], v[92:93], v[102:103], v[46:47] op_sel_hi:[0,1,1]
	v_pk_fma_f32 v[42:43], v[92:93], v[102:103], v[42:43] op_sel:[1,0,0]
	v_pk_fma_f32 v[34:35], v[94:95], v[102:103], v[34:35] op_sel_hi:[0,1,1]
	v_pk_fma_f32 v[26:27], v[94:95], v[102:103], v[26:27] op_sel:[1,0,0]
	v_pk_fma_f32 v[40:41], v[92:93], v[104:105], v[40:41] op_sel_hi:[0,1,1]
	v_pk_fma_f32 v[32:33], v[92:93], v[104:105], v[32:33] op_sel:[1,0,0]
	v_pk_fma_f32 v[22:23], v[94:95], v[104:105], v[22:23] op_sel_hi:[0,1,1]
	v_pk_fma_f32 v[18:19], v[94:95], v[104:105], v[18:19] op_sel:[1,0,0]
	v_pk_fma_f32 v[36:37], v[92:93], v[106:107], v[36:37] op_sel_hi:[0,1,1]
	v_pk_fma_f32 v[28:29], v[92:93], v[106:107], v[28:29] op_sel:[1,0,0]
	v_pk_fma_f32 v[20:21], v[94:95], v[106:107], v[20:21] op_sel_hi:[0,1,1]
	v_pk_fma_f32 v[16:17], v[94:95], v[106:107], v[16:17] op_sel:[1,0,0]
	ds_read_b128 v[92:95], v87 offset:3328
	s_waitcnt vmcnt(12) lgkmcnt(1)
; DI void attn_item(const P& p, int b, int kvh, int quad4, char* smem, const AttnPre& pre) {
;     ...
;     for (int u = 0; u < 16; ++u) vv[u] = *(const uint2*)(vb + (size_t)idx[n0 + 4 * u + quad] * 256);
; #pragma unroll
;     for (int u = 0; u < 16; ++u) {
;       const float4 p4 = *(const float4*)(L + (n0 + 4 * u + quad) * 4);
;       const f32x2_t c0 = __builtin_amdgcn_cvt_pk_f32_fp8((int)vv[u].x, false), c1 = __builtin_amdgcn_cvt_pk_f32_fp8((int)vv[u].x, true);
;       const f32x2_t c2 = __builtin_amdgcn_cvt_pk_f32_fp8((int)vv[u].y, false), c3 = __builtin_amdgcn_cvt_pk_f32_fp8((int)vv[u].y, true);
;       const float vf[8] = {c0.x, c0.y, c1.x, c1.y, c2.x, c2.y, c3.x, c3.y};
; #pragma unroll
;       for (int e = 0; e < 8; ++e) {
;         o[0][e] = fmaf(p4.x, vf[e], o[0][e]); o[1][e] = fmaf(p4.y, vf[e], o[1][e]);
;         o[2][e] = fmaf(p4.z, vf[e], o[2][e]); o[3][e] = fmaf(p4.w, vf[e], o[3][e]);
;       }
	v_cvt_pk_f32_fp8_e32 v[100:101], v126
	v_cvt_pk_f32_fp8_sdwa v[102:103], v126 src0_sel:WORD_1
	v_cvt_pk_f32_fp8_e32 v[104:105], v127
	v_cvt_pk_f32_fp8_sdwa v[106:107], v127 src0_sel:WORD_1
	v_pk_fma_f32 v[48:49], v[96:97], v[100:101], v[48:49] op_sel_hi:[0,1,1]
	v_pk_fma_f32 v[44:45], v[96:97], v[100:101], v[44:45] op_sel:[1,0,0]
	v_pk_fma_f32 v[38:39], v[98:99], v[100:101], v[38:39] op_sel_hi:[0,1,1]
	v_pk_fma_f32 v[30:31], v[98:99], v[100:101], v[30:31] op_sel:[1,0,0]
	v_pk_fma_f32 v[46:47], v[96:97], v[102:103], v[46:47] op_sel_hi:[0,1,1]
	v_pk_fma_f32 v[42:43], v[96:97], v[102:103], v[42:43] op_sel:[1,0,0]
	v_pk_fma_f32 v[34:35], v[98:99], v[102:103], v[34:35] op_sel_hi:[0,1,1]
	v_pk_fma_f32 v[26:27], v[98:99], v[102:103], v[26:27] op_sel:[1,0,0]
	v_pk_fma_f32 v[40:41], v[96:97], v[104:105], v[40:41] op_sel_hi:[0,1,1]
	v_pk_fma_f32 v[32:33], v[96:97], v[104:105], v[32:33] op_sel:[1,0,0]
	v_pk_fma_f32 v[22:23], v[98:99], v[104:105], v[22:23] op_sel_hi:[0,1,1]
	v_pk_fma_f32 v[18:19], v[98:99], v[104:105], v[18:19] op_sel:[1,0,0]
	v_pk_fma_f32 v[36:37], v[96:97], v[106:107], v[36:37] op_sel_hi:[0,1,1]
	v_pk_fma_f32 v[28:29], v[96:97], v[106:107], v[28:29] op_sel:[1,0,0]
	v_pk_fma_f32 v[20:21], v[98:99], v[106:107], v[20:21] op_sel_hi:[0,1,1]
	v_pk_fma_f32 v[16:17], v[98:99], v[106:107], v[16:17] op_sel:[1,0,0]
	ds_read_b128 v[96:99], v87 offset:3392
	s_waitcnt vmcnt(11) lgkmcnt(1)
	v_cvt_pk_f32_fp8_e32 v[100:101], v128
	v_cvt_pk_f32_fp8_sdwa v[102:103], v128 src0_sel:WORD_1
	v_cvt_pk_f32_fp8_e32 v[104:105], v129
	v_cvt_pk_f32_fp8_sdwa v[106:107], v129 src0_sel:WORD_1
	v_pk_fma_f32 v[48:49], v[92:93], v[100:101], v[48:49] op_sel_hi:[0,1,1]
	v_pk_fma_f32 v[44:45], v[92:93], v[100:101], v[44:45] op_sel:[1,0,0]
	v_pk_fma_f32 v[38:39], v[94:95], v[100:101], v[38:39] op_sel_hi:[0,1,1]
	v_pk_fma_f32 v[30:31], v[94:95], v[100:101], v[30:31] op_sel:[1,0,0]
	v_pk_fma_f32 v[46:47], v[92:93], v[102:103], v[46:47] op_sel_hi:[0,1,1]
	v_pk_fma_f32 v[42:43], v[92:93], v[102:103], v[42:43] op_sel:[1,0,0]
	v_pk_fma_f32 v[34:35], v[94:95], v[102:103], v[34:35] op_sel_hi:[0,1,1]
	v_pk_fma_f32 v[26:27], v[94:95], v[102:103], v[26:27] op_sel:[1,0,0]
	v_pk_fma_f32 v[40:41], v[92:93], v[104:105], v[40:41] op_sel_hi:[0,1,1]
	v_pk_fma_f32 v[32:33], v[92:93], v[104:105], v[32:33] op_sel:[1,0,0]
	v_pk_fma_f32 v[22:23], v[94:95], v[104:105], v[22:23] op_sel_hi:[0,1,1]
	v_pk_fma_f32 v[18:19], v[94:95], v[104:105], v[18:19] op_sel:[1,0,0]
	v_pk_fma_f32 v[36:37], v[92:93], v[106:107], v[36:37] op_sel_hi:[0,1,1]
	v_pk_fma_f32 v[28:29], v[92:93], v[106:107], v[28:29] op_sel:[1,0,0]
	v_pk_fma_f32 v[20:21], v[94:95], v[106:107], v[20:21] op_sel_hi:[0,1,1]
	v_pk_fma_f32 v[16:17], v[94:95], v[106:107], v[16:17] op_sel:[1,0,0]
	ds_read_b128 v[92:95], v87 offset:3456
	s_waitcnt vmcnt(10) lgkmcnt(1)
	v_cvt_pk_f32_fp8_e32 v[100:101], v130
	v_cvt_pk_f32_fp8_sdwa v[102:103], v130 src0_sel:WORD_1
	v_cvt_pk_f32_fp8_e32 v[104:105], v131
	v_cvt_pk_f32_fp8_sdwa v[106:107], v131 src0_sel:WORD_1
	v_pk_fma_f32 v[48:49], v[96:97], v[100:101], v[48:49] op_sel_hi:[0,1,1]
	v_pk_fma_f32 v[44:45], v[96:97], v[100:101], v[44:45] op_sel:[1,0,0]
	v_pk_fma_f32 v[38:39], v[98:99], v[100:101], v[38:39] op_sel_hi:[0,1,1]
	v_pk_fma_f32 v[30:31], v[98:99], v[100:101], v[30:31] op_sel:[1,0,0]
	v_pk_fma_f32 v[46:47], v[96:97], v[102:103], v[46:47] op_sel_hi:[0,1,1]
	v_pk_fma_f32 v[42:43], v[96:97], v[102:103], v[42:43] op_sel:[1,0,0]
	v_pk_fma_f32 v[34:35], v[98:99], v[102:103], v[34:35] op_sel_hi:[0,1,1]
	v_pk_fma_f32 v[26:27], v[98:99], v[102:103], v[26:27] op_sel:[1,0,0]
	v_pk_fma_f32 v[40:41], v[96:97], v[104:105], v[40:41] op_sel_hi:[0,1,1]
	v_pk_fma_f32 v[32:33], v[96:97], v[104:105], v[32:33] op_sel:[1,0,0]
	v_pk_fma_f32 v[22:23], v[98:99], v[104:105], v[22:23] op_sel_hi:[0,1,1]
	v_pk_fma_f32 v[18:19], v[98:99], v[104:105], v[18:19] op_sel:[1,0,0]
	v_pk_fma_f32 v[36:37], v[96:97], v[106:107], v[36:37] op_sel_hi:[0,1,1]
	v_pk_fma_f32 v[28:29], v[96:97], v[106:107], v[28:29] op_sel:[1,0,0]
	v_pk_fma_f32 v[20:21], v[98:99], v[106:107], v[20:21] op_sel_hi:[0,1,1]
	v_pk_fma_f32 v[16:17], v[98:99], v[106:107], v[16:17] op_sel:[1,0,0]
	ds_read_b128 v[96:99], v87 offset:3520
	s_waitcnt vmcnt(9) lgkmcnt(1)
	v_cvt_pk_f32_fp8_e32 v[100:101], v132
	v_cvt_pk_f32_fp8_sdwa v[102:103], v132 src0_sel:WORD_1
	v_cvt_pk_f32_fp8_e32 v[104:105], v133
	v_cvt_pk_f32_fp8_sdwa v[106:107], v133 src0_sel:WORD_1
	v_pk_fma_f32 v[48:49], v[92:93], v[100:101], v[48:49] op_sel_hi:[0,1,1]
	v_pk_fma_f32 v[44:45], v[92:93], v[100:101], v[44:45] op_sel:[1,0,0]
	v_pk_fma_f32 v[38:39], v[94:95], v[100:101], v[38:39] op_sel_hi:[0,1,1]
	v_pk_fma_f32 v[30:31], v[94:95], v[100:101], v[30:31] op_sel:[1,0,0]
	v_pk_fma_f32 v[46:47], v[92:93], v[102:103], v[46:47] op_sel_hi:[0,1,1]
	v_pk_fma_f32 v[42:43], v[92:93], v[102:103], v[42:43] op_sel:[1,0,0]
	v_pk_fma_f32 v[34:35], v[94:95], v[102:103], v[34:35] op_sel_hi:[0,1,1]
	v_pk_fma_f32 v[26:27], v[94:95], v[102:103], v[26:27] op_sel:[1,0,0]
	v_pk_fma_f32 v[40:41], v[92:93], v[104:105], v[40:41] op_sel_hi:[0,1,1]
	v_pk_fma_f32 v[32:33], v[92:93], v[104:105], v[32:33] op_sel:[1,0,0]
	v_pk_fma_f32 v[22:23], v[94:95], v[104:105], v[22:23] op_sel_hi:[0,1,1]
	v_pk_fma_f32 v[18:19], v[94:95], v[104:105], v[18:19] op_sel:[1,0,0]
	v_pk_fma_f32 v[36:37], v[92:93], v[106:107], v[36:37] op_sel_hi:[0,1,1]
	v_pk_fma_f32 v[28:29], v[92:93], v[106:107], v[28:29] op_sel:[1,0,0]
	v_pk_fma_f32 v[20:21], v[94:95], v[106:107], v[20:21] op_sel_hi:[0,1,1]
	v_pk_fma_f32 v[16:17], v[94:95], v[106:107], v[16:17] op_sel:[1,0,0]
	ds_read_b128 v[92:95], v87 offset:3584
	s_waitcnt vmcnt(8) lgkmcnt(1)
; DI void attn_item(const P& p, int b, int kvh, int quad4, char* smem, const AttnPre& pre) {
;     ...
;     for (int u = 0; u < 16; ++u) vv[u] = *(const uint2*)(vb + (size_t)idx[n0 + 4 * u + quad] * 256);
; #pragma unroll
;     for (int u = 0; u < 16; ++u) {
;       const float4 p4 = *(const float4*)(L + (n0 + 4 * u + quad) * 4);
;       const f32x2_t c0 = __builtin_amdgcn_cvt_pk_f32_fp8((int)vv[u].x, false), c1 = __builtin_amdgcn_cvt_pk_f32_fp8((int)vv[u].x, true);
;       const f32x2_t c2 = __builtin_amdgcn_cvt_pk_f32_fp8((int)vv[u].y, false), c3 = __builtin_amdgcn_cvt_pk_f32_fp8((int)vv[u].y, true);
;       const float vf[8] = {c0.x, c0.y, c1.x, c1.y, c2.x, c2.y, c3.x, c3.y};
; #pragma unroll
;       for (int e = 0; e < 8; ++e) {
;         o[0][e] = fmaf(p4.x, vf[e], o[0][e]); o[1][e] = fmaf(p4.y, vf[e], o[1][e]);
;         o[2][e] = fmaf(p4.z, vf[e], o[2][e]); o[3][e] = fmaf(p4.w, vf[e], o[3][e]);
;       }
	v_cvt_pk_f32_fp8_e32 v[100:101], v134
	v_cvt_pk_f32_fp8_sdwa v[102:103], v134 src0_sel:WORD_1
	v_cvt_pk_f32_fp8_e32 v[104:105], v135
	v_cvt_pk_f32_fp8_sdwa v[106:107], v135 src0_sel:WORD_1
	v_pk_fma_f32 v[48:49], v[96:97], v[100:101], v[48:49] op_sel_hi:[0,1,1]
	v_pk_fma_f32 v[44:45], v[96:97], v[100:101], v[44:45] op_sel:[1,0,0]
	v_pk_fma_f32 v[38:39], v[98:99], v[100:101], v[38:39] op_sel_hi:[0,1,1]
	v_pk_fma_f32 v[30:31], v[98:99], v[100:101], v[30:31] op_sel:[1,0,0]
	v_pk_fma_f32 v[46:47], v[96:97], v[102:103], v[46:47] op_sel_hi:[0,1,1]
	v_pk_fma_f32 v[42:43], v[96:97], v[102:103], v[42:43] op_sel:[1,0,0]
	v_pk_fma_f32 v[34:35], v[98:99], v[102:103], v[34:35] op_sel_hi:[0,1,1]
	v_pk_fma_f32 v[26:27], v[98:99], v[102:103], v[26:27] op_sel:[1,0,0]
	v_pk_fma_f32 v[40:41], v[96:97], v[104:105], v[40:41] op_sel_hi:[0,1,1]
	v_pk_fma_f32 v[32:33], v[96:97], v[104:105], v[32:33] op_sel:[1,0,0]
	v_pk_fma_f32 v[22:23], v[98:99], v[104:105], v[22:23] op_sel_hi:[0,1,1]
	v_pk_fma_f32 v[18:19], v[98:99], v[104:105], v[18:19] op_sel:[1,0,0]
	v_pk_fma_f32 v[36:37], v[96:97], v[106:107], v[36:37] op_sel_hi:[0,1,1]
	v_pk_fma_f32 v[28:29], v[96:97], v[106:107], v[28:29] op_sel:[1,0,0]
	v_pk_fma_f32 v[20:21], v[98:99], v[106:107], v[20:21] op_sel_hi:[0,1,1]
	v_pk_fma_f32 v[16:17], v[98:99], v[106:107], v[16:17] op_sel:[1,0,0]
	ds_read_b128 v[96:99], v87 offset:3648
	s_waitcnt vmcnt(7) lgkmcnt(1)
	v_cvt_pk_f32_fp8_e32 v[100:101], v136
	v_cvt_pk_f32_fp8_sdwa v[102:103], v136 src0_sel:WORD_1
	v_cvt_pk_f32_fp8_e32 v[104:105], v137
	v_cvt_pk_f32_fp8_sdwa v[106:107], v137 src0_sel:WORD_1
	v_pk_fma_f32 v[48:49], v[92:93], v[100:101], v[48:49] op_sel_hi:[0,1,1]
	v_pk_fma_f32 v[44:45], v[92:93], v[100:101], v[44:45] op_sel:[1,0,0]
	v_pk_fma_f32 v[38:39], v[94:95], v[100:101], v[38:39] op_sel_hi:[0,1,1]
	v_pk_fma_f32 v[30:31], v[94:95], v[100:101], v[30:31] op_sel:[1,0,0]
	v_pk_fma_f32 v[46:47], v[92:93], v[102:103], v[46:47] op_sel_hi:[0,1,1]
	v_pk_fma_f32 v[42:43], v[92:93], v[102:103], v[42:43] op_sel:[1,0,0]
	v_pk_fma_f32 v[34:35], v[94:95], v[102:103], v[34:35] op_sel_hi:[0,1,1]
	v_pk_fma_f32 v[26:27], v[94:95], v[102:103], v[26:27] op_sel:[1,0,0]
	v_pk_fma_f32 v[40:41], v[92:93], v[104:105], v[40:41] op_sel_hi:[0,1,1]
	v_pk_fma_f32 v[32:33], v[92:93], v[104:105], v[32:33] op_sel:[1,0,0]
	v_pk_fma_f32 v[22:23], v[94:95], v[104:105], v[22:23] op_sel_hi:[0,1,1]
	v_pk_fma_f32 v[18:19], v[94:95], v[104:105], v[18:19] op_sel:[1,0,0]
	v_pk_fma_f32 v[36:37], v[92:93], v[106:107], v[36:37] op_sel_hi:[0,1,1]
	v_pk_fma_f32 v[28:29], v[92:93], v[106:107], v[28:29] op_sel:[1,0,0]
	v_pk_fma_f32 v[20:21], v[94:95], v[106:107], v[20:21] op_sel_hi:[0,1,1]
	v_pk_fma_f32 v[16:17], v[94:95], v[106:107], v[16:17] op_sel:[1,0,0]
	ds_read_b128 v[92:95], v87 offset:3712
	s_waitcnt vmcnt(6) lgkmcnt(1)
	v_cvt_pk_f32_fp8_e32 v[100:101], v138
	v_cvt_pk_f32_fp8_sdwa v[102:103], v138 src0_sel:WORD_1
	v_cvt_pk_f32_fp8_e32 v[104:105], v139
	v_cvt_pk_f32_fp8_sdwa v[106:107], v139 src0_sel:WORD_1
	v_pk_fma_f32 v[48:49], v[96:97], v[100:101], v[48:49] op_sel_hi:[0,1,1]
	v_pk_fma_f32 v[44:45], v[96:97], v[100:101], v[44:45] op_sel:[1,0,0]
	v_pk_fma_f32 v[38:39], v[98:99], v[100:101], v[38:39] op_sel_hi:[0,1,1]
	v_pk_fma_f32 v[30:31], v[98:99], v[100:101], v[30:31] op_sel:[1,0,0]
	v_pk_fma_f32 v[46:47], v[96:97], v[102:103], v[46:47] op_sel_hi:[0,1,1]
	v_pk_fma_f32 v[42:43], v[96:97], v[102:103], v[42:43] op_sel:[1,0,0]
	v_pk_fma_f32 v[34:35], v[98:99], v[102:103], v[34:35] op_sel_hi:[0,1,1]
	v_pk_fma_f32 v[26:27], v[98:99], v[102:103], v[26:27] op_sel:[1,0,0]
	v_pk_fma_f32 v[40:41], v[96:97], v[104:105], v[40:41] op_sel_hi:[0,1,1]
	v_pk_fma_f32 v[32:33], v[96:97], v[104:105], v[32:33] op_sel:[1,0,0]
	v_pk_fma_f32 v[22:23], v[98:99], v[104:105], v[22:23] op_sel_hi:[0,1,1]
	v_pk_fma_f32 v[18:19], v[98:99], v[104:105], v[18:19] op_sel:[1,0,0]
	v_pk_fma_f32 v[36:37], v[96:97], v[106:107], v[36:37] op_sel_hi:[0,1,1]
	v_pk_fma_f32 v[28:29], v[96:97], v[106:107], v[28:29] op_sel:[1,0,0]
	v_pk_fma_f32 v[20:21], v[98:99], v[106:107], v[20:21] op_sel_hi:[0,1,1]
	v_pk_fma_f32 v[16:17], v[98:99], v[106:107], v[16:17] op_sel:[1,0,0]
	ds_read_b128 v[96:99], v87 offset:3776
	s_waitcnt vmcnt(5) lgkmcnt(1)
	v_cvt_pk_f32_fp8_e32 v[100:101], v140
	v_cvt_pk_f32_fp8_sdwa v[102:103], v140 src0_sel:WORD_1
	v_cvt_pk_f32_fp8_e32 v[104:105], v141
	v_cvt_pk_f32_fp8_sdwa v[106:107], v141 src0_sel:WORD_1
	v_pk_fma_f32 v[48:49], v[92:93], v[100:101], v[48:49] op_sel_hi:[0,1,1]
	v_pk_fma_f32 v[44:45], v[92:93], v[100:101], v[44:45] op_sel:[1,0,0]
	v_pk_fma_f32 v[38:39], v[94:95], v[100:101], v[38:39] op_sel_hi:[0,1,1]
	v_pk_fma_f32 v[30:31], v[94:95], v[100:101], v[30:31] op_sel:[1,0,0]
	v_pk_fma_f32 v[46:47], v[92:93], v[102:103], v[46:47] op_sel_hi:[0,1,1]
	v_pk_fma_f32 v[42:43], v[92:93], v[102:103], v[42:43] op_sel:[1,0,0]
	v_pk_fma_f32 v[34:35], v[94:95], v[102:103], v[34:35] op_sel_hi:[0,1,1]
	v_pk_fma_f32 v[26:27], v[94:95], v[102:103], v[26:27] op_sel:[1,0,0]
	v_pk_fma_f32 v[40:41], v[92:93], v[104:105], v[40:41] op_sel_hi:[0,1,1]
	v_pk_fma_f32 v[32:33], v[92:93], v[104:105], v[32:33] op_sel:[1,0,0]
	v_pk_fma_f32 v[22:23], v[94:95], v[104:105], v[22:23] op_sel_hi:[0,1,1]
	v_pk_fma_f32 v[18:19], v[94:95], v[104:105], v[18:19] op_sel:[1,0,0]
	v_pk_fma_f32 v[36:37], v[92:93], v[106:107], v[36:37] op_sel_hi:[0,1,1]
	v_pk_fma_f32 v[28:29], v[92:93], v[106:107], v[28:29] op_sel:[1,0,0]
	v_pk_fma_f32 v[20:21], v[94:95], v[106:107], v[20:21] op_sel_hi:[0,1,1]
	v_pk_fma_f32 v[16:17], v[94:95], v[106:107], v[16:17] op_sel:[1,0,0]
	ds_read_b128 v[92:95], v87 offset:3840
	s_waitcnt vmcnt(4) lgkmcnt(1)
; DI void attn_item(const P& p, int b, int kvh, int quad4, char* smem, const AttnPre& pre) {
;     ...
;     for (int u = 0; u < 16; ++u) vv[u] = *(const uint2*)(vb + (size_t)idx[n0 + 4 * u + quad] * 256);
; #pragma unroll
;     for (int u = 0; u < 16; ++u) {
;       const float4 p4 = *(const float4*)(L + (n0 + 4 * u + quad) * 4);
;       const f32x2_t c0 = __builtin_amdgcn_cvt_pk_f32_fp8((int)vv[u].x, false), c1 = __builtin_amdgcn_cvt_pk_f32_fp8((int)vv[u].x, true);
;       const f32x2_t c2 = __builtin_amdgcn_cvt_pk_f32_fp8((int)vv[u].y, false), c3 = __builtin_amdgcn_cvt_pk_f32_fp8((int)vv[u].y, true);
;       const float vf[8] = {c0.x, c0.y, c1.x, c1.y, c2.x, c2.y, c3.x, c3.y};
; #pragma unroll
;       for (int e = 0; e < 8; ++e) {
;         o[0][e] = fmaf(p4.x, vf[e], o[0][e]); o[1][e] = fmaf(p4.y, vf[e], o[1][e]);
;         o[2][e] = fmaf(p4.z, vf[e], o[2][e]); o[3][e] = fmaf(p4.w, vf[e], o[3][e]);
;       }
	v_cvt_pk_f32_fp8_e32 v[100:101], v142
	v_cvt_pk_f32_fp8_sdwa v[102:103], v142 src0_sel:WORD_1
	v_cvt_pk_f32_fp8_e32 v[104:105], v143
	v_cvt_pk_f32_fp8_sdwa v[106:107], v143 src0_sel:WORD_1
	v_pk_fma_f32 v[48:49], v[96:97], v[100:101], v[48:49] op_sel_hi:[0,1,1]
	v_pk_fma_f32 v[44:45], v[96:97], v[100:101], v[44:45] op_sel:[1,0,0]
	v_pk_fma_f32 v[38:39], v[98:99], v[100:101], v[38:39] op_sel_hi:[0,1,1]
	v_pk_fma_f32 v[30:31], v[98:99], v[100:101], v[30:31] op_sel:[1,0,0]
	v_pk_fma_f32 v[46:47], v[96:97], v[102:103], v[46:47] op_sel_hi:[0,1,1]
	v_pk_fma_f32 v[42:43], v[96:97], v[102:103], v[42:43] op_sel:[1,0,0]
	v_pk_fma_f32 v[34:35], v[98:99], v[102:103], v[34:35] op_sel_hi:[0,1,1]
	v_pk_fma_f32 v[26:27], v[98:99], v[102:103], v[26:27] op_sel:[1,0,0]
	v_pk_fma_f32 v[40:41], v[96:97], v[104:105], v[40:41] op_sel_hi:[0,1,1]
	v_pk_fma_f32 v[32:33], v[96:97], v[104:105], v[32:33] op_sel:[1,0,0]
	v_pk_fma_f32 v[22:23], v[98:99], v[104:105], v[22:23] op_sel_hi:[0,1,1]
	v_pk_fma_f32 v[18:19], v[98:99], v[104:105], v[18:19] op_sel:[1,0,0]
	v_pk_fma_f32 v[36:37], v[96:97], v[106:107], v[36:37] op_sel_hi:[0,1,1]
	v_pk_fma_f32 v[28:29], v[96:97], v[106:107], v[28:29] op_sel:[1,0,0]
	v_pk_fma_f32 v[20:21], v[98:99], v[106:107], v[20:21] op_sel_hi:[0,1,1]
	v_pk_fma_f32 v[16:17], v[98:99], v[106:107], v[16:17] op_sel:[1,0,0]
	ds_read_b128 v[96:99], v87 offset:3904
	s_waitcnt vmcnt(3) lgkmcnt(1)
	v_cvt_pk_f32_fp8_e32 v[100:101], v144
	v_cvt_pk_f32_fp8_sdwa v[102:103], v144 src0_sel:WORD_1
	v_cvt_pk_f32_fp8_e32 v[104:105], v145
	v_cvt_pk_f32_fp8_sdwa v[106:107], v145 src0_sel:WORD_1
	v_pk_fma_f32 v[48:49], v[92:93], v[100:101], v[48:49] op_sel_hi:[0,1,1]
	v_pk_fma_f32 v[44:45], v[92:93], v[100:101], v[44:45] op_sel:[1,0,0]
	v_pk_fma_f32 v[38:39], v[94:95], v[100:101], v[38:39] op_sel_hi:[0,1,1]
	v_pk_fma_f32 v[30:31], v[94:95], v[100:101], v[30:31] op_sel:[1,0,0]
	v_pk_fma_f32 v[46:47], v[92:93], v[102:103], v[46:47] op_sel_hi:[0,1,1]
	v_pk_fma_f32 v[42:43], v[92:93], v[102:103], v[42:43] op_sel:[1,0,0]
	v_pk_fma_f32 v[34:35], v[94:95], v[102:103], v[34:35] op_sel_hi:[0,1,1]
	v_pk_fma_f32 v[26:27], v[94:95], v[102:103], v[26:27] op_sel:[1,0,0]
	v_pk_fma_f32 v[40:41], v[92:93], v[104:105], v[40:41] op_sel_hi:[0,1,1]
	v_pk_fma_f32 v[32:33], v[92:93], v[104:105], v[32:33] op_sel:[1,0,0]
	v_pk_fma_f32 v[22:23], v[94:95], v[104:105], v[22:23] op_sel_hi:[0,1,1]
	v_pk_fma_f32 v[18:19], v[94:95], v[104:105], v[18:19] op_sel:[1,0,0]
	v_pk_fma_f32 v[36:37], v[92:93], v[106:107], v[36:37] op_sel_hi:[0,1,1]
	v_pk_fma_f32 v[28:29], v[92:93], v[106:107], v[28:29] op_sel:[1,0,0]
	v_pk_fma_f32 v[20:21], v[94:95], v[106:107], v[20:21] op_sel_hi:[0,1,1]
	v_pk_fma_f32 v[16:17], v[94:95], v[106:107], v[16:17] op_sel:[1,0,0]
	ds_read_b128 v[92:95], v87 offset:3968
	s_waitcnt vmcnt(2) lgkmcnt(1)
	v_cvt_pk_f32_fp8_e32 v[100:101], v146
	v_cvt_pk_f32_fp8_sdwa v[102:103], v146 src0_sel:WORD_1
	v_cvt_pk_f32_fp8_e32 v[104:105], v147
	v_cvt_pk_f32_fp8_sdwa v[106:107], v147 src0_sel:WORD_1
	v_pk_fma_f32 v[48:49], v[96:97], v[100:101], v[48:49] op_sel_hi:[0,1,1]
	v_pk_fma_f32 v[44:45], v[96:97], v[100:101], v[44:45] op_sel:[1,0,0]
	v_pk_fma_f32 v[38:39], v[98:99], v[100:101], v[38:39] op_sel_hi:[0,1,1]
	v_pk_fma_f32 v[30:31], v[98:99], v[100:101], v[30:31] op_sel:[1,0,0]
	v_pk_fma_f32 v[46:47], v[96:97], v[102:103], v[46:47] op_sel_hi:[0,1,1]
	v_pk_fma_f32 v[42:43], v[96:97], v[102:103], v[42:43] op_sel:[1,0,0]
	v_pk_fma_f32 v[34:35], v[98:99], v[102:103], v[34:35] op_sel_hi:[0,1,1]
	v_pk_fma_f32 v[26:27], v[98:99], v[102:103], v[26:27] op_sel:[1,0,0]
	v_pk_fma_f32 v[40:41], v[96:97], v[104:105], v[40:41] op_sel_hi:[0,1,1]
	v_pk_fma_f32 v[32:33], v[96:97], v[104:105], v[32:33] op_sel:[1,0,0]
	v_pk_fma_f32 v[22:23], v[98:99], v[104:105], v[22:23] op_sel_hi:[0,1,1]
	v_pk_fma_f32 v[18:19], v[98:99], v[104:105], v[18:19] op_sel:[1,0,0]
	v_pk_fma_f32 v[36:37], v[96:97], v[106:107], v[36:37] op_sel_hi:[0,1,1]
	v_pk_fma_f32 v[28:29], v[96:97], v[106:107], v[28:29] op_sel:[1,0,0]
	v_pk_fma_f32 v[20:21], v[98:99], v[106:107], v[20:21] op_sel_hi:[0,1,1]
	v_pk_fma_f32 v[16:17], v[98:99], v[106:107], v[16:17] op_sel:[1,0,0]
	ds_read_b128 v[96:99], v87 offset:4032
	s_waitcnt vmcnt(1) lgkmcnt(1)
	v_cvt_pk_f32_fp8_e32 v[100:101], v148
	v_cvt_pk_f32_fp8_sdwa v[102:103], v148 src0_sel:WORD_1
	v_cvt_pk_f32_fp8_e32 v[104:105], v149
	v_cvt_pk_f32_fp8_sdwa v[106:107], v149 src0_sel:WORD_1
	v_pk_fma_f32 v[48:49], v[92:93], v[100:101], v[48:49] op_sel_hi:[0,1,1]
	v_pk_fma_f32 v[44:45], v[92:93], v[100:101], v[44:45] op_sel:[1,0,0]
	v_pk_fma_f32 v[38:39], v[94:95], v[100:101], v[38:39] op_sel_hi:[0,1,1]
	v_pk_fma_f32 v[30:31], v[94:95], v[100:101], v[30:31] op_sel:[1,0,0]
	v_pk_fma_f32 v[46:47], v[92:93], v[102:103], v[46:47] op_sel_hi:[0,1,1]
	v_pk_fma_f32 v[42:43], v[92:93], v[102:103], v[42:43] op_sel:[1,0,0]
	v_pk_fma_f32 v[34:35], v[94:95], v[102:103], v[34:35] op_sel_hi:[0,1,1]
	v_pk_fma_f32 v[26:27], v[94:95], v[102:103], v[26:27] op_sel:[1,0,0]
	v_pk_fma_f32 v[40:41], v[92:93], v[104:105], v[40:41] op_sel_hi:[0,1,1]
	v_pk_fma_f32 v[32:33], v[92:93], v[104:105], v[32:33] op_sel:[1,0,0]
	v_pk_fma_f32 v[22:23], v[94:95], v[104:105], v[22:23] op_sel_hi:[0,1,1]
	v_pk_fma_f32 v[18:19], v[94:95], v[104:105], v[18:19] op_sel:[1,0,0]
	v_pk_fma_f32 v[36:37], v[92:93], v[106:107], v[36:37] op_sel_hi:[0,1,1]
	v_pk_fma_f32 v[28:29], v[92:93], v[106:107], v[28:29] op_sel:[1,0,0]
	v_pk_fma_f32 v[20:21], v[94:95], v[106:107], v[20:21] op_sel_hi:[0,1,1]
	v_pk_fma_f32 v[16:17], v[94:95], v[106:107], v[16:17] op_sel:[1,0,0]
	s_waitcnt vmcnt(0) lgkmcnt(0)
; DI uint4 pack8(const float* v) { uint4 r; r.x = pack2(v[0], v[1]); r.y = pack2(v[2], v[3]); r.z = pack2(v[4], v[5]); r.w = pack2(v[6], v[7]); return r; }
; DI void attn_item(const P& p, int b, int kvh, int quad4, char* smem, const AttnPre& pre) {
;     ...
;     for (int u = 0; u < 16; ++u) {
;       const float4 p4 = *(const float4*)(L + (n0 + 4 * u + quad) * 4);
;       const f32x2_t c0 = __builtin_amdgcn_cvt_pk_f32_fp8((int)vv[u].x, false), c1 = __builtin_amdgcn_cvt_pk_f32_fp8((int)vv[u].x, true);
;       const f32x2_t c2 = __builtin_amdgcn_cvt_pk_f32_fp8((int)vv[u].y, false), c3 = __builtin_amdgcn_cvt_pk_f32_fp8((int)vv[u].y, true);
;       const float vf[8] = {c0.x, c0.y, c1.x, c1.y, c2.x, c2.y, c3.x, c3.y};
; #pragma unroll
;       for (int e = 0; e < 8; ++e) {
;         o[0][e] = fmaf(p4.x, vf[e], o[0][e]); o[1][e] = fmaf(p4.y, vf[e], o[1][e]);
;         o[2][e] = fmaf(p4.z, vf[e], o[2][e]); o[3][e] = fmaf(p4.w, vf[e], o[3][e]);
;       }
;     }
;   }
; #pragma unroll
;   for (int h = 0; h < 4; ++h)
; #pragma unroll
;     for (int e = 0; e < 8; ++e) { float v = o[h][e]; v += __shfl_xor(v, 16); v += __shfl_xor(v, 32); o[h][e] = v; }
;   if (quad == 0) {
; #pragma unroll
;     for (int h = 0; h < 4; ++h) *(uint4*)(p.q + tok * 1024 + (kvh * 4 + h) * 128 + r * 8) = pack8(o[h]);
;   }
	v_cvt_pk_f32_fp8_e32 v[100:101], v150
	v_cvt_pk_f32_fp8_sdwa v[102:103], v150 src0_sel:WORD_1
	v_cvt_pk_f32_fp8_e32 v[104:105], v151
	v_cvt_pk_f32_fp8_sdwa v[106:107], v151 src0_sel:WORD_1
	v_pk_fma_f32 v[48:49], v[96:97], v[100:101], v[48:49] op_sel_hi:[0,1,1]
	v_pk_fma_f32 v[44:45], v[96:97], v[100:101], v[44:45] op_sel:[1,0,0]
	v_pk_fma_f32 v[38:39], v[98:99], v[100:101], v[38:39] op_sel_hi:[0,1,1]
	v_pk_fma_f32 v[30:31], v[98:99], v[100:101], v[30:31] op_sel:[1,0,0]
	v_pk_fma_f32 v[46:47], v[96:97], v[102:103], v[46:47] op_sel_hi:[0,1,1]
	v_pk_fma_f32 v[42:43], v[96:97], v[102:103], v[42:43] op_sel:[1,0,0]
	v_pk_fma_f32 v[34:35], v[98:99], v[102:103], v[34:35] op_sel_hi:[0,1,1]
	v_pk_fma_f32 v[26:27], v[98:99], v[102:103], v[26:27] op_sel:[1,0,0]
	v_pk_fma_f32 v[40:41], v[96:97], v[104:105], v[40:41] op_sel_hi:[0,1,1]
	v_pk_fma_f32 v[32:33], v[96:97], v[104:105], v[32:33] op_sel:[1,0,0]
	v_pk_fma_f32 v[22:23], v[98:99], v[104:105], v[22:23] op_sel_hi:[0,1,1]
	v_pk_fma_f32 v[18:19], v[98:99], v[104:105], v[18:19] op_sel:[1,0,0]
	v_pk_fma_f32 v[36:37], v[96:97], v[106:107], v[36:37] op_sel_hi:[0,1,1]
	v_pk_fma_f32 v[28:29], v[96:97], v[106:107], v[28:29] op_sel:[1,0,0]
	v_pk_fma_f32 v[20:21], v[98:99], v[106:107], v[20:21] op_sel_hi:[0,1,1]
	v_pk_fma_f32 v[16:17], v[98:99], v[106:107], v[16:17] op_sel:[1,0,0]
	ds_bpermute_b32 v24, v85, v48
	ds_bpermute_b32 v25, v85, v49
	ds_bpermute_b32 v50, v85, v46
	ds_bpermute_b32 v51, v85, v47
	ds_bpermute_b32 v52, v85, v40
	ds_bpermute_b32 v53, v85, v41
	ds_bpermute_b32 v54, v85, v36
	ds_bpermute_b32 v55, v85, v37
	ds_bpermute_b32 v56, v85, v44
	ds_bpermute_b32 v57, v85, v45
	ds_bpermute_b32 v58, v85, v42
	ds_bpermute_b32 v59, v85, v43
	ds_bpermute_b32 v60, v85, v32
	ds_bpermute_b32 v61, v85, v33
	ds_bpermute_b32 v62, v85, v28
	ds_bpermute_b32 v63, v85, v29
	ds_bpermute_b32 v64, v85, v38
	ds_bpermute_b32 v65, v85, v39
	ds_bpermute_b32 v66, v85, v34
	ds_bpermute_b32 v67, v85, v35
	ds_bpermute_b32 v68, v85, v22
	ds_bpermute_b32 v69, v85, v23
	ds_bpermute_b32 v70, v85, v20
	ds_bpermute_b32 v71, v85, v21
	ds_bpermute_b32 v72, v85, v30
	ds_bpermute_b32 v73, v85, v31
	ds_bpermute_b32 v74, v85, v26
	ds_bpermute_b32 v75, v85, v27
	ds_bpermute_b32 v76, v85, v18
	ds_bpermute_b32 v77, v85, v19
	ds_bpermute_b32 v78, v85, v16
	ds_bpermute_b32 v79, v85, v17
	s_waitcnt lgkmcnt(14)
	v_pk_add_f32 v[24:25], v[48:49], v[24:25]
	v_pk_add_f32 v[46:47], v[46:47], v[50:51]
	v_pk_add_f32 v[40:41], v[40:41], v[52:53]
	v_pk_add_f32 v[36:37], v[36:37], v[54:55]
	v_pk_add_f32 v[44:45], v[44:45], v[56:57]
	v_pk_add_f32 v[42:43], v[42:43], v[58:59]
	v_pk_add_f32 v[32:33], v[32:33], v[60:61]
	v_pk_add_f32 v[28:29], v[28:29], v[62:63]
	v_pk_add_f32 v[38:39], v[38:39], v[64:65]
	s_waitcnt lgkmcnt(12)
	v_pk_add_f32 v[34:35], v[34:35], v[66:67]
	s_waitcnt lgkmcnt(10)
	v_pk_add_f32 v[22:23], v[22:23], v[68:69]
	s_waitcnt lgkmcnt(8)
	v_pk_add_f32 v[20:21], v[20:21], v[70:71]
	s_waitcnt lgkmcnt(6)
	v_pk_add_f32 v[30:31], v[30:31], v[72:73]
	s_waitcnt lgkmcnt(4)
	v_pk_add_f32 v[26:27], v[26:27], v[74:75]
	s_waitcnt lgkmcnt(2)
	v_pk_add_f32 v[18:19], v[18:19], v[76:77]
	s_waitcnt lgkmcnt(0)
	v_pk_add_f32 v[16:17], v[16:17], v[78:79]
	ds_bpermute_b32 v48, v84, v24
	ds_bpermute_b32 v49, v84, v25
	ds_bpermute_b32 v50, v84, v46
	ds_bpermute_b32 v51, v84, v47
	ds_bpermute_b32 v52, v84, v40
	ds_bpermute_b32 v53, v84, v41
	ds_bpermute_b32 v54, v84, v36
	ds_bpermute_b32 v55, v84, v37
	ds_bpermute_b32 v56, v84, v44
	ds_bpermute_b32 v57, v84, v45
	ds_bpermute_b32 v58, v84, v42
	ds_bpermute_b32 v59, v84, v43
	ds_bpermute_b32 v60, v84, v32
	ds_bpermute_b32 v61, v84, v33
	ds_bpermute_b32 v62, v84, v28
	ds_bpermute_b32 v63, v84, v29
	ds_bpermute_b32 v64, v84, v38
	ds_bpermute_b32 v65, v84, v39
	ds_bpermute_b32 v66, v84, v34
	ds_bpermute_b32 v67, v84, v35
	ds_bpermute_b32 v68, v84, v22
	ds_bpermute_b32 v69, v84, v23
	ds_bpermute_b32 v70, v84, v20
	ds_bpermute_b32 v71, v84, v21
	ds_bpermute_b32 v72, v84, v30
	ds_bpermute_b32 v73, v84, v31
	ds_bpermute_b32 v74, v84, v26
	ds_bpermute_b32 v75, v84, v27
	ds_bpermute_b32 v76, v84, v18
	ds_bpermute_b32 v77, v84, v19
	ds_bpermute_b32 v78, v84, v16
	ds_bpermute_b32 v79, v84, v17
	s_and_saveexec_b64 s[6:7], s[4:5]
	s_cbranch_execz .LBB0_304
	v_readlane_b32 s10, v250, 17
	s_waitcnt lgkmcnt(0)
	v_pk_add_f32 v[78:79], v[16:17], v[78:79]
	v_pk_add_f32 v[16:17], v[24:25], v[48:49]
	v_lshlrev_b64 v[24:25], 11, v[90:91]
	s_lshl_b32 s4, s9, 9
	v_readlane_b32 s11, v250, 18
	s_ashr_i32 s5, s4, 31
	v_pk_add_f32 v[76:77], v[18:19], v[76:77]
	v_lshl_add_u64 v[24:25], s[10:11], 0, v[24:25]
	v_pk_add_f32 v[36:37], v[36:37], v[54:55]
	v_pk_add_f32 v[18:19], v[40:41], v[52:53]
	v_pk_add_f32 v[40:41], v[46:47], v[50:51]
	v_lshl_add_u64 v[24:25], s[4:5], 1, v[24:25]
	v_lshlrev_b32_e32 v192, 1, v192
	v_pk_add_f32 v[28:29], v[28:29], v[62:63]
	v_pk_add_f32 v[32:33], v[32:33], v[60:61]
	v_pk_add_f32 v[42:43], v[42:43], v[58:59]
	v_pk_add_f32 v[44:45], v[44:45], v[56:57]
	v_cvt_pk_bf16_f32 v16, v16, v17
	v_cvt_pk_bf16_f32 v17, v40, v41
	v_cvt_pk_bf16_f32 v18, v18, v19
	v_cvt_pk_bf16_f32 v19, v36, v37
	v_lshl_add_u64 v[24:25], v[24:25], 0, v[192:193]
	v_pk_add_f32 v[20:21], v[20:21], v[70:71]
	v_pk_add_f32 v[22:23], v[22:23], v[68:69]
	v_pk_add_f32 v[34:35], v[34:35], v[66:67]
	v_pk_add_f32 v[38:39], v[38:39], v[64:65]
	global_store_dwordx4 v[24:25], v[16:19], off
	v_pk_add_f32 v[26:27], v[26:27], v[74:75]
	v_pk_add_f32 v[30:31], v[30:31], v[72:73]
	v_cvt_pk_bf16_f32 v16, v44, v45
	v_cvt_pk_bf16_f32 v17, v42, v43
	v_cvt_pk_bf16_f32 v18, v32, v33
	v_cvt_pk_bf16_f32 v19, v28, v29
	global_store_dwordx4 v[24:25], v[16:19], off offset:256
	s_nop 1
	v_cvt_pk_bf16_f32 v16, v38, v39
	v_cvt_pk_bf16_f32 v17, v34, v35
	v_cvt_pk_bf16_f32 v18, v22, v23
	v_cvt_pk_bf16_f32 v19, v20, v21
	global_store_dwordx4 v[24:25], v[16:19], off offset:512
	s_nop 1
	v_cvt_pk_bf16_f32 v16, v30, v31
	v_cvt_pk_bf16_f32 v17, v26, v27
	v_cvt_pk_bf16_f32 v18, v76, v77
	v_cvt_pk_bf16_f32 v19, v78, v79
	global_store_dwordx4 v[24:25], v[16:19], off offset:768
	s_branch .LBB0_304
